# attention Q fragments prefetched one tile ahead; ffn_fixup rewritten by hand with all loads in flight
# speedup vs baseline: 1.0136x; 1.0136x over previous
.LBB0_37:
	s_ashr_i32 s0, s21, 3
	s_add_i32 s0, s23, s0
	s_ashr_i32 s1, s0, 31
	s_lshr_b32 s1, s1, 27
	s_add_i32 s1, s0, s1
	s_ashr_i32 s21, s1, 5
	s_lshl_b32 s37, s21, 3
	s_sub_i32 s21, 0x80, s37
	s_min_i32 s21, s21, 8
	s_abs_i32 s21, s21
	v_cvt_f32_u32_e32 v0, s21
	s_sub_i32 s22, 0, s21
	s_andn2_b32 s1, s1, 31
	s_sub_i32 s0, s0, s1
	v_rcp_iflag_f32_e32 v0, v0
	s_ashr_i32 s1, s0, 31
	s_abs_i32 s0, s0
	v_mul_f32_e32 v0, 0x4f7ffffe, v0
	v_cvt_u32_f32_e32 v0, v0
	s_nop 0
	v_readfirstlane_b32 s23, v0
	s_mul_i32 s22, s22, s23
	s_mul_hi_u32 s22, s23, s22
	s_add_i32 s23, s23, s22
	s_mul_hi_u32 s22, s0, s23
	s_mul_i32 s22, s22, s21
	s_sub_i32 s0, s0, s22
	s_sub_i32 s22, s0, s21
	s_cmp_ge_u32 s0, s21
	s_cselect_b32 s0, s22, s0
	s_sub_i32 s22, s0, s21
	s_cmp_ge_u32 s0, s21
	s_cselect_b32 s0, s22, s0
	s_xor_b32 s0, s0, s1
	s_sub_i32 s0, s0, s1
	s_add_i32 s37, s37, s0
	s_cmp_lg_u32 s37, s20
	s_cbranch_scc0 .LBB0_30
	v_cmp_gt_u32_e32 vcc, 0x160, v197
	s_and_saveexec_b64 s[0:1], vcc
	s_cbranch_execz .LBB0_29
	v_readlane_b32 s22, v252, 2
	v_readlane_b32 s23, v252, 3
	v_readlane_b32 s24, v252, 4
	v_readlane_b32 s25, v252, 5
	v_readlane_b32 s2, v252, 14
	v_readlane_b32 s3, v252, 15
	s_lshl_b32 s42, s37, 2
	v_lshlrev_b32_e32 v236, 4, v197
	v_lshlrev_b32_e32 v240, 5, v197
	v_add_u32_e32 v237, 0x1600, v236
	v_add_u32_e32 v238, 0x2c00, v236
	v_add_u32_e32 v239, 0x4200, v236
	v_add_u32_e32 v241, 0x5800, v240
	v_add_u32_e32 v242, 0xb000, v240
	v_add_u32_e32 v243, 0x2c00, v240
	v_add_u32_e32 v244, 0x2c00, v241
	v_add_u32_e32 v245, 0x2c00, v242
	global_load_dwordx4 v[4:7], v240, s[24:25]
	global_load_dwordx4 v[8:11], v240, s[24:25] offset:16
	global_load_dwordx4 v[12:15], v243, s[24:25]
	global_load_dwordx4 v[16:19], v243, s[24:25] offset:16
	global_load_dwordx4 v[20:23], v240, s[22:23]
	global_load_dwordx4 v[24:27], v240, s[22:23] offset:16
	global_load_dwordx4 v[28:31], v241, s[22:23]
	global_load_dwordx4 v[32:35], v241, s[22:23] offset:16
	global_load_dwordx4 v[36:39], v242, s[22:23]
	global_load_dwordx4 v[40:43], v242, s[22:23] offset:16
	global_load_dwordx4 v[44:47], v243, s[22:23]
	global_load_dwordx4 v[48:51], v243, s[22:23] offset:16
	global_load_dwordx4 v[52:55], v244, s[22:23]
	global_load_dwordx4 v[56:59], v244, s[22:23] offset:16
	global_load_dwordx4 v[60:63], v245, s[22:23]
	global_load_dwordx4 v[64:67], v245, s[22:23] offset:16
	s_add_i32 s40, s42, 0
	s_mul_i32 s41, s40, 0xb000
	s_add_u32 s20, s56, s41
	s_addc_u32 s21, s57, 0
	s_add_u32 s26, s20, 0xffff5000
	s_addc_u32 s27, s21, -1
	s_add_u32 s20, s20, 0x5800
	s_addc_u32 s21, s21, 0
	s_and_b32 s41, s37, 15
	s_cmp_eq_u32 s41, 0
	s_cselect_b32 s26, s2, s26
	s_cselect_b32 s27, s3, s27
	global_load_dwordx4 v[68:71], v236, s[26:27]
	global_load_dwordx4 v[72:75], v238, s[26:27]
	global_load_dwordx4 v[76:79], v236, s[20:21]
	global_load_dwordx4 v[80:83], v238, s[20:21]
	global_load_dwordx4 v[84:87], v237, s[26:27]
	global_load_dwordx4 v[88:91], v239, s[26:27]
	global_load_dwordx4 v[92:95], v237, s[20:21]
	global_load_dwordx4 v[96:99], v239, s[20:21]
	s_add_i32 s40, s42, 1
	s_mul_i32 s41, s40, 0xb000
	s_add_u32 s20, s56, s41
	s_addc_u32 s21, s57, 0
	s_add_u32 s26, s20, 0xffff5000
	s_addc_u32 s27, s21, -1
	s_add_u32 s20, s20, 0x5800
	s_addc_u32 s21, s21, 0
	global_load_dwordx4 v[100:103], v236, s[26:27]
	global_load_dwordx4 v[104:107], v238, s[26:27]
	global_load_dwordx4 v[108:111], v236, s[20:21]
	global_load_dwordx4 v[112:115], v238, s[20:21]
	global_load_dwordx4 v[116:119], v237, s[26:27]
	global_load_dwordx4 v[120:123], v239, s[26:27]
	global_load_dwordx4 v[124:127], v237, s[20:21]
	global_load_dwordx4 v[128:131], v239, s[20:21]
	s_add_i32 s40, s42, 2
	s_mul_i32 s41, s40, 0xb000
	s_add_u32 s20, s56, s41
	s_addc_u32 s21, s57, 0
	s_add_u32 s26, s20, 0xffff5000
	s_addc_u32 s27, s21, -1
	s_add_u32 s20, s20, 0x5800
	s_addc_u32 s21, s21, 0
	global_load_dwordx4 v[132:135], v236, s[26:27]
	global_load_dwordx4 v[136:139], v238, s[26:27]
	global_load_dwordx4 v[140:143], v236, s[20:21]
	global_load_dwordx4 v[144:147], v238, s[20:21]
	global_load_dwordx4 v[148:151], v237, s[26:27]
	global_load_dwordx4 v[152:155], v239, s[26:27]
	global_load_dwordx4 v[156:159], v237, s[20:21]
	global_load_dwordx4 v[160:163], v239, s[20:21]
	s_add_i32 s40, s42, 3
	s_mul_i32 s41, s40, 0xb000
	s_add_u32 s20, s56, s41
	s_addc_u32 s21, s57, 0
	s_add_u32 s26, s20, 0xffff5000
	s_addc_u32 s27, s21, -1
	s_add_u32 s20, s20, 0x5800
	s_addc_u32 s21, s21, 0
	global_load_dwordx4 v[164:167], v236, s[26:27]
	global_load_dwordx4 v[168:171], v238, s[26:27]
	global_load_dwordx4 v[172:175], v236, s[20:21]
	global_load_dwordx4 v[176:179], v238, s[20:21]
	global_load_dwordx4 v[180:183], v237, s[26:27]
	global_load_dwordx4 v[184:187], v239, s[26:27]
	global_load_dwordx4 v[188:191], v237, s[20:21]
	global_load_dwordx4 v[192:195], v239, s[20:21]
	s_mov_b32 s40, 0xbfb8aa3b
	s_mov_b32 s41, 0xbfb8aa3b
	s_waitcnt vmcnt(24)
	v_lshlrev_b32_e32 v198, 16, v68
	v_and_b32_e32 v199, 0xffff0000, v68
	v_lshlrev_b32_e32 v200, 16, v72
	v_and_b32_e32 v201, 0xffff0000, v72
	v_lshlrev_b32_e32 v202, 16, v76
	v_and_b32_e32 v203, 0xffff0000, v76
	v_lshlrev_b32_e32 v204, 16, v80
	v_and_b32_e32 v205, 0xffff0000, v80
	v_lshlrev_b32_e32 v206, 16, v84
	v_and_b32_e32 v207, 0xffff0000, v84
	v_lshlrev_b32_e32 v208, 16, v88
	v_and_b32_e32 v209, 0xffff0000, v88
	v_lshlrev_b32_e32 v210, 16, v92
	v_and_b32_e32 v211, 0xffff0000, v92
	v_lshlrev_b32_e32 v212, 16, v96
	v_and_b32_e32 v213, 0xffff0000, v96
	v_pk_fma_f32 v[246:247], v[36:37], v[202:203], v[4:5]
	v_pk_fma_f32 v[214:215], v[60:61], v[210:211], v[12:13]
	v_pk_fma_f32 v[248:249], v[36:37], v[204:205], v[4:5]
	v_pk_fma_f32 v[216:217], v[60:61], v[212:213], v[12:13]
	v_pk_fma_f32 v[246:247], v[28:29], v[200:201], v[246:247]
	v_pk_fma_f32 v[214:215], v[52:53], v[208:209], v[214:215]
	v_pk_fma_f32 v[248:249], v[28:29], v[202:203], v[248:249]
	v_pk_fma_f32 v[216:217], v[52:53], v[210:211], v[216:217]
	v_pk_fma_f32 v[246:247], v[20:21], v[198:199], v[246:247]
	v_pk_fma_f32 v[214:215], v[44:45], v[206:207], v[214:215]
	v_pk_fma_f32 v[248:249], v[20:21], v[200:201], v[248:249]
	v_pk_fma_f32 v[216:217], v[44:45], v[208:209], v[216:217]
	v_pk_mul_f32 v[198:199], v[246:247], s[40:41]
	v_pk_mul_f32 v[200:201], v[248:249], s[40:41]
	v_exp_f32_e32 v198, v198
	v_exp_f32_e32 v199, v199
	v_exp_f32_e32 v200, v200
	v_exp_f32_e32 v201, v201
	v_pk_mul_f32 v[214:215], v[214:215], v[246:247]
	v_pk_mul_f32 v[216:217], v[216:217], v[248:249]
	v_pk_add_f32 v[198:199], v[198:199], 1.0 op_sel_hi:[1,0]
	v_pk_add_f32 v[200:201], v[200:201], 1.0 op_sel_hi:[1,0]
	v_rcp_f32_e32 v198, v198
	v_rcp_f32_e32 v199, v199
	v_rcp_f32_e32 v200, v200
	v_rcp_f32_e32 v201, v201
	s_nop 0
	v_pk_mul_f32 v[214:215], v[214:215], v[198:199]
	v_pk_mul_f32 v[216:217], v[216:217], v[200:201]
	v_cvt_pk_bf16_f32 v68, v214, v215
	v_cvt_pk_bf16_f32 v72, v216, v217
	v_lshlrev_b32_e32 v198, 16, v69
	v_and_b32_e32 v199, 0xffff0000, v69
	v_lshlrev_b32_e32 v200, 16, v73
	v_and_b32_e32 v201, 0xffff0000, v73
	v_lshlrev_b32_e32 v202, 16, v77
	v_and_b32_e32 v203, 0xffff0000, v77
	v_lshlrev_b32_e32 v204, 16, v81
	v_and_b32_e32 v205, 0xffff0000, v81
	v_lshlrev_b32_e32 v206, 16, v85
	v_and_b32_e32 v207, 0xffff0000, v85
	v_lshlrev_b32_e32 v208, 16, v89
	v_and_b32_e32 v209, 0xffff0000, v89
	v_lshlrev_b32_e32 v210, 16, v93
	v_and_b32_e32 v211, 0xffff0000, v93
	v_lshlrev_b32_e32 v212, 16, v97
	v_and_b32_e32 v213, 0xffff0000, v97
	v_pk_fma_f32 v[246:247], v[38:39], v[202:203], v[6:7]
	v_pk_fma_f32 v[214:215], v[62:63], v[210:211], v[14:15]
	v_pk_fma_f32 v[248:249], v[38:39], v[204:205], v[6:7]
	v_pk_fma_f32 v[216:217], v[62:63], v[212:213], v[14:15]
	v_pk_fma_f32 v[246:247], v[30:31], v[200:201], v[246:247]
	v_pk_fma_f32 v[214:215], v[54:55], v[208:209], v[214:215]
	v_pk_fma_f32 v[248:249], v[30:31], v[202:203], v[248:249]
	v_pk_fma_f32 v[216:217], v[54:55], v[210:211], v[216:217]
	v_pk_fma_f32 v[246:247], v[22:23], v[198:199], v[246:247]
	v_pk_fma_f32 v[214:215], v[46:47], v[206:207], v[214:215]
	v_pk_fma_f32 v[248:249], v[22:23], v[200:201], v[248:249]
	v_pk_fma_f32 v[216:217], v[46:47], v[208:209], v[216:217]
	v_pk_mul_f32 v[198:199], v[246:247], s[40:41]
	v_pk_mul_f32 v[200:201], v[248:249], s[40:41]
	v_exp_f32_e32 v198, v198
	v_exp_f32_e32 v199, v199
	v_exp_f32_e32 v200, v200
	v_exp_f32_e32 v201, v201
	v_pk_mul_f32 v[214:215], v[214:215], v[246:247]
	v_pk_mul_f32 v[216:217], v[216:217], v[248:249]
	v_pk_add_f32 v[198:199], v[198:199], 1.0 op_sel_hi:[1,0]
	v_pk_add_f32 v[200:201], v[200:201], 1.0 op_sel_hi:[1,0]
	v_rcp_f32_e32 v198, v198
	v_rcp_f32_e32 v199, v199
	v_rcp_f32_e32 v200, v200
	v_rcp_f32_e32 v201, v201
	s_nop 0
	v_pk_mul_f32 v[214:215], v[214:215], v[198:199]
	v_pk_mul_f32 v[216:217], v[216:217], v[200:201]
	v_cvt_pk_bf16_f32 v69, v214, v215
	v_cvt_pk_bf16_f32 v73, v216, v217
	v_lshlrev_b32_e32 v198, 16, v70
	v_and_b32_e32 v199, 0xffff0000, v70
	v_lshlrev_b32_e32 v200, 16, v74
	v_and_b32_e32 v201, 0xffff0000, v74
	v_lshlrev_b32_e32 v202, 16, v78
	v_and_b32_e32 v203, 0xffff0000, v78
	v_lshlrev_b32_e32 v204, 16, v82
	v_and_b32_e32 v205, 0xffff0000, v82
	v_lshlrev_b32_e32 v206, 16, v86
	v_and_b32_e32 v207, 0xffff0000, v86
	v_lshlrev_b32_e32 v208, 16, v90
	v_and_b32_e32 v209, 0xffff0000, v90
	v_lshlrev_b32_e32 v210, 16, v94
	v_and_b32_e32 v211, 0xffff0000, v94
	v_lshlrev_b32_e32 v212, 16, v98
	v_and_b32_e32 v213, 0xffff0000, v98
	v_pk_fma_f32 v[246:247], v[40:41], v[202:203], v[8:9]
	v_pk_fma_f32 v[214:215], v[64:65], v[210:211], v[16:17]
	v_pk_fma_f32 v[248:249], v[40:41], v[204:205], v[8:9]
	v_pk_fma_f32 v[216:217], v[64:65], v[212:213], v[16:17]
	v_pk_fma_f32 v[246:247], v[32:33], v[200:201], v[246:247]
	v_pk_fma_f32 v[214:215], v[56:57], v[208:209], v[214:215]
	v_pk_fma_f32 v[248:249], v[32:33], v[202:203], v[248:249]
	v_pk_fma_f32 v[216:217], v[56:57], v[210:211], v[216:217]
	v_pk_fma_f32 v[246:247], v[24:25], v[198:199], v[246:247]
	v_pk_fma_f32 v[214:215], v[48:49], v[206:207], v[214:215]
	v_pk_fma_f32 v[248:249], v[24:25], v[200:201], v[248:249]
	v_pk_fma_f32 v[216:217], v[48:49], v[208:209], v[216:217]
	v_pk_mul_f32 v[198:199], v[246:247], s[40:41]
	v_pk_mul_f32 v[200:201], v[248:249], s[40:41]
	v_exp_f32_e32 v198, v198
	v_exp_f32_e32 v199, v199
	v_exp_f32_e32 v200, v200
	v_exp_f32_e32 v201, v201
	v_pk_mul_f32 v[214:215], v[214:215], v[246:247]
	v_pk_mul_f32 v[216:217], v[216:217], v[248:249]
	v_pk_add_f32 v[198:199], v[198:199], 1.0 op_sel_hi:[1,0]
	v_pk_add_f32 v[200:201], v[200:201], 1.0 op_sel_hi:[1,0]
	v_rcp_f32_e32 v198, v198
	v_rcp_f32_e32 v199, v199
	v_rcp_f32_e32 v200, v200
	v_rcp_f32_e32 v201, v201
	s_nop 0
	v_pk_mul_f32 v[214:215], v[214:215], v[198:199]
	v_pk_mul_f32 v[216:217], v[216:217], v[200:201]
	v_cvt_pk_bf16_f32 v70, v214, v215
	v_cvt_pk_bf16_f32 v74, v216, v217
	v_lshlrev_b32_e32 v198, 16, v71
	v_and_b32_e32 v199, 0xffff0000, v71
	v_lshlrev_b32_e32 v200, 16, v75
	v_and_b32_e32 v201, 0xffff0000, v75
	v_lshlrev_b32_e32 v202, 16, v79
	v_and_b32_e32 v203, 0xffff0000, v79
	v_lshlrev_b32_e32 v204, 16, v83
	v_and_b32_e32 v205, 0xffff0000, v83
	v_lshlrev_b32_e32 v206, 16, v87
	v_and_b32_e32 v207, 0xffff0000, v87
	v_lshlrev_b32_e32 v208, 16, v91
	v_and_b32_e32 v209, 0xffff0000, v91
	v_lshlrev_b32_e32 v210, 16, v95
	v_and_b32_e32 v211, 0xffff0000, v95
	v_lshlrev_b32_e32 v212, 16, v99
	v_and_b32_e32 v213, 0xffff0000, v99
	v_pk_fma_f32 v[246:247], v[42:43], v[202:203], v[10:11]
	v_pk_fma_f32 v[214:215], v[66:67], v[210:211], v[18:19]
	v_pk_fma_f32 v[248:249], v[42:43], v[204:205], v[10:11]
	v_pk_fma_f32 v[216:217], v[66:67], v[212:213], v[18:19]
	v_pk_fma_f32 v[246:247], v[34:35], v[200:201], v[246:247]
	v_pk_fma_f32 v[214:215], v[58:59], v[208:209], v[214:215]
	v_pk_fma_f32 v[248:249], v[34:35], v[202:203], v[248:249]
	v_pk_fma_f32 v[216:217], v[58:59], v[210:211], v[216:217]
	v_pk_fma_f32 v[246:247], v[26:27], v[198:199], v[246:247]
	v_pk_fma_f32 v[214:215], v[50:51], v[206:207], v[214:215]
	v_pk_fma_f32 v[248:249], v[26:27], v[200:201], v[248:249]
	v_pk_fma_f32 v[216:217], v[50:51], v[208:209], v[216:217]
	v_pk_mul_f32 v[198:199], v[246:247], s[40:41]
	v_pk_mul_f32 v[200:201], v[248:249], s[40:41]
	v_exp_f32_e32 v198, v198
	v_exp_f32_e32 v199, v199
	v_exp_f32_e32 v200, v200
	v_exp_f32_e32 v201, v201
	v_pk_mul_f32 v[214:215], v[214:215], v[246:247]
	v_pk_mul_f32 v[216:217], v[216:217], v[248:249]
	v_pk_add_f32 v[198:199], v[198:199], 1.0 op_sel_hi:[1,0]
	v_pk_add_f32 v[200:201], v[200:201], 1.0 op_sel_hi:[1,0]
	v_rcp_f32_e32 v198, v198
	v_rcp_f32_e32 v199, v199
	v_rcp_f32_e32 v200, v200
	v_rcp_f32_e32 v201, v201
	s_nop 0
	v_pk_mul_f32 v[214:215], v[214:215], v[198:199]
	v_pk_mul_f32 v[216:217], v[216:217], v[200:201]
	v_cvt_pk_bf16_f32 v71, v214, v215
	v_cvt_pk_bf16_f32 v75, v216, v217
	s_add_i32 s38, s42, 0
	s_mul_i32 s39, s38, 0x58000
	s_add_u32 s38, s82, s39
	s_addc_u32 s39, s83, 0
	global_store_dwordx4 v236, v[68:71], s[38:39]
	global_store_dwordx4 v237, v[72:75], s[38:39]
	s_waitcnt vmcnt(18)
	v_lshlrev_b32_e32 v198, 16, v100
	v_and_b32_e32 v199, 0xffff0000, v100
	v_lshlrev_b32_e32 v200, 16, v104
	v_and_b32_e32 v201, 0xffff0000, v104
	v_lshlrev_b32_e32 v202, 16, v108
	v_and_b32_e32 v203, 0xffff0000, v108
	v_lshlrev_b32_e32 v204, 16, v112
	v_and_b32_e32 v205, 0xffff0000, v112
	v_lshlrev_b32_e32 v206, 16, v116
	v_and_b32_e32 v207, 0xffff0000, v116
	v_lshlrev_b32_e32 v208, 16, v120
	v_and_b32_e32 v209, 0xffff0000, v120
	v_lshlrev_b32_e32 v210, 16, v124
	v_and_b32_e32 v211, 0xffff0000, v124
	v_lshlrev_b32_e32 v212, 16, v128
	v_and_b32_e32 v213, 0xffff0000, v128
	v_pk_fma_f32 v[246:247], v[36:37], v[202:203], v[4:5]
	v_pk_fma_f32 v[214:215], v[60:61], v[210:211], v[12:13]
	v_pk_fma_f32 v[248:249], v[36:37], v[204:205], v[4:5]
	v_pk_fma_f32 v[216:217], v[60:61], v[212:213], v[12:13]
	v_pk_fma_f32 v[246:247], v[28:29], v[200:201], v[246:247]
	v_pk_fma_f32 v[214:215], v[52:53], v[208:209], v[214:215]
	v_pk_fma_f32 v[248:249], v[28:29], v[202:203], v[248:249]
	v_pk_fma_f32 v[216:217], v[52:53], v[210:211], v[216:217]
	v_pk_fma_f32 v[246:247], v[20:21], v[198:199], v[246:247]
	v_pk_fma_f32 v[214:215], v[44:45], v[206:207], v[214:215]
	v_pk_fma_f32 v[248:249], v[20:21], v[200:201], v[248:249]
	v_pk_fma_f32 v[216:217], v[44:45], v[208:209], v[216:217]
	v_pk_mul_f32 v[198:199], v[246:247], s[40:41]
	v_pk_mul_f32 v[200:201], v[248:249], s[40:41]
	v_exp_f32_e32 v198, v198
	v_exp_f32_e32 v199, v199
	v_exp_f32_e32 v200, v200
	v_exp_f32_e32 v201, v201
	v_pk_mul_f32 v[214:215], v[214:215], v[246:247]
	v_pk_mul_f32 v[216:217], v[216:217], v[248:249]
	v_pk_add_f32 v[198:199], v[198:199], 1.0 op_sel_hi:[1,0]
	v_pk_add_f32 v[200:201], v[200:201], 1.0 op_sel_hi:[1,0]
	v_rcp_f32_e32 v198, v198
	v_rcp_f32_e32 v199, v199
	v_rcp_f32_e32 v200, v200
	v_rcp_f32_e32 v201, v201
	s_nop 0
	v_pk_mul_f32 v[214:215], v[214:215], v[198:199]
	v_pk_mul_f32 v[216:217], v[216:217], v[200:201]
	v_cvt_pk_bf16_f32 v100, v214, v215
	v_cvt_pk_bf16_f32 v104, v216, v217
	v_lshlrev_b32_e32 v198, 16, v101
	v_and_b32_e32 v199, 0xffff0000, v101
	v_lshlrev_b32_e32 v200, 16, v105
	v_and_b32_e32 v201, 0xffff0000, v105
	v_lshlrev_b32_e32 v202, 16, v109
	v_and_b32_e32 v203, 0xffff0000, v109
	v_lshlrev_b32_e32 v204, 16, v113
	v_and_b32_e32 v205, 0xffff0000, v113
	v_lshlrev_b32_e32 v206, 16, v117
	v_and_b32_e32 v207, 0xffff0000, v117
	v_lshlrev_b32_e32 v208, 16, v121
	v_and_b32_e32 v209, 0xffff0000, v121
	v_lshlrev_b32_e32 v210, 16, v125
	v_and_b32_e32 v211, 0xffff0000, v125
	v_lshlrev_b32_e32 v212, 16, v129
	v_and_b32_e32 v213, 0xffff0000, v129
	v_pk_fma_f32 v[246:247], v[38:39], v[202:203], v[6:7]
	v_pk_fma_f32 v[214:215], v[62:63], v[210:211], v[14:15]
	v_pk_fma_f32 v[248:249], v[38:39], v[204:205], v[6:7]
	v_pk_fma_f32 v[216:217], v[62:63], v[212:213], v[14:15]
	v_pk_fma_f32 v[246:247], v[30:31], v[200:201], v[246:247]
	v_pk_fma_f32 v[214:215], v[54:55], v[208:209], v[214:215]
	v_pk_fma_f32 v[248:249], v[30:31], v[202:203], v[248:249]
	v_pk_fma_f32 v[216:217], v[54:55], v[210:211], v[216:217]
	v_pk_fma_f32 v[246:247], v[22:23], v[198:199], v[246:247]
	v_pk_fma_f32 v[214:215], v[46:47], v[206:207], v[214:215]
	v_pk_fma_f32 v[248:249], v[22:23], v[200:201], v[248:249]
	v_pk_fma_f32 v[216:217], v[46:47], v[208:209], v[216:217]
	v_pk_mul_f32 v[198:199], v[246:247], s[40:41]
	v_pk_mul_f32 v[200:201], v[248:249], s[40:41]
	v_exp_f32_e32 v198, v198
	v_exp_f32_e32 v199, v199
	v_exp_f32_e32 v200, v200
	v_exp_f32_e32 v201, v201
	v_pk_mul_f32 v[214:215], v[214:215], v[246:247]
	v_pk_mul_f32 v[216:217], v[216:217], v[248:249]
	v_pk_add_f32 v[198:199], v[198:199], 1.0 op_sel_hi:[1,0]
	v_pk_add_f32 v[200:201], v[200:201], 1.0 op_sel_hi:[1,0]
	v_rcp_f32_e32 v198, v198
	v_rcp_f32_e32 v199, v199
	v_rcp_f32_e32 v200, v200
	v_rcp_f32_e32 v201, v201
	s_nop 0
	v_pk_mul_f32 v[214:215], v[214:215], v[198:199]
	v_pk_mul_f32 v[216:217], v[216:217], v[200:201]
	v_cvt_pk_bf16_f32 v101, v214, v215
	v_cvt_pk_bf16_f32 v105, v216, v217
	v_lshlrev_b32_e32 v198, 16, v102
	v_and_b32_e32 v199, 0xffff0000, v102
	v_lshlrev_b32_e32 v200, 16, v106
	v_and_b32_e32 v201, 0xffff0000, v106
	v_lshlrev_b32_e32 v202, 16, v110
	v_and_b32_e32 v203, 0xffff0000, v110
	v_lshlrev_b32_e32 v204, 16, v114
	v_and_b32_e32 v205, 0xffff0000, v114
	v_lshlrev_b32_e32 v206, 16, v118
	v_and_b32_e32 v207, 0xffff0000, v118
	v_lshlrev_b32_e32 v208, 16, v122
	v_and_b32_e32 v209, 0xffff0000, v122
	v_lshlrev_b32_e32 v210, 16, v126
	v_and_b32_e32 v211, 0xffff0000, v126
	v_lshlrev_b32_e32 v212, 16, v130
	v_and_b32_e32 v213, 0xffff0000, v130
	v_pk_fma_f32 v[246:247], v[40:41], v[202:203], v[8:9]
	v_pk_fma_f32 v[214:215], v[64:65], v[210:211], v[16:17]
	v_pk_fma_f32 v[248:249], v[40:41], v[204:205], v[8:9]
	v_pk_fma_f32 v[216:217], v[64:65], v[212:213], v[16:17]
	v_pk_fma_f32 v[246:247], v[32:33], v[200:201], v[246:247]
	v_pk_fma_f32 v[214:215], v[56:57], v[208:209], v[214:215]
	v_pk_fma_f32 v[248:249], v[32:33], v[202:203], v[248:249]
	v_pk_fma_f32 v[216:217], v[56:57], v[210:211], v[216:217]
	v_pk_fma_f32 v[246:247], v[24:25], v[198:199], v[246:247]
	v_pk_fma_f32 v[214:215], v[48:49], v[206:207], v[214:215]
	v_pk_fma_f32 v[248:249], v[24:25], v[200:201], v[248:249]
	v_pk_fma_f32 v[216:217], v[48:49], v[208:209], v[216:217]
	v_pk_mul_f32 v[198:199], v[246:247], s[40:41]
	v_pk_mul_f32 v[200:201], v[248:249], s[40:41]
	v_exp_f32_e32 v198, v198
	v_exp_f32_e32 v199, v199
	v_exp_f32_e32 v200, v200
	v_exp_f32_e32 v201, v201
	v_pk_mul_f32 v[214:215], v[214:215], v[246:247]
	v_pk_mul_f32 v[216:217], v[216:217], v[248:249]
	v_pk_add_f32 v[198:199], v[198:199], 1.0 op_sel_hi:[1,0]
	v_pk_add_f32 v[200:201], v[200:201], 1.0 op_sel_hi:[1,0]
	v_rcp_f32_e32 v198, v198
	v_rcp_f32_e32 v199, v199
	v_rcp_f32_e32 v200, v200
	v_rcp_f32_e32 v201, v201
	s_nop 0
	v_pk_mul_f32 v[214:215], v[214:215], v[198:199]
	v_pk_mul_f32 v[216:217], v[216:217], v[200:201]
	v_cvt_pk_bf16_f32 v102, v214, v215
	v_cvt_pk_bf16_f32 v106, v216, v217
	v_lshlrev_b32_e32 v198, 16, v103
	v_and_b32_e32 v199, 0xffff0000, v103
	v_lshlrev_b32_e32 v200, 16, v107
	v_and_b32_e32 v201, 0xffff0000, v107
	v_lshlrev_b32_e32 v202, 16, v111
	v_and_b32_e32 v203, 0xffff0000, v111
	v_lshlrev_b32_e32 v204, 16, v115
	v_and_b32_e32 v205, 0xffff0000, v115
	v_lshlrev_b32_e32 v206, 16, v119
	v_and_b32_e32 v207, 0xffff0000, v119
	v_lshlrev_b32_e32 v208, 16, v123
	v_and_b32_e32 v209, 0xffff0000, v123
	v_lshlrev_b32_e32 v210, 16, v127
	v_and_b32_e32 v211, 0xffff0000, v127
	v_lshlrev_b32_e32 v212, 16, v131
	v_and_b32_e32 v213, 0xffff0000, v131
	v_pk_fma_f32 v[246:247], v[42:43], v[202:203], v[10:11]
	v_pk_fma_f32 v[214:215], v[66:67], v[210:211], v[18:19]
	v_pk_fma_f32 v[248:249], v[42:43], v[204:205], v[10:11]
	v_pk_fma_f32 v[216:217], v[66:67], v[212:213], v[18:19]
	v_pk_fma_f32 v[246:247], v[34:35], v[200:201], v[246:247]
	v_pk_fma_f32 v[214:215], v[58:59], v[208:209], v[214:215]
	v_pk_fma_f32 v[248:249], v[34:35], v[202:203], v[248:249]
	v_pk_fma_f32 v[216:217], v[58:59], v[210:211], v[216:217]
	v_pk_fma_f32 v[246:247], v[26:27], v[198:199], v[246:247]
	v_pk_fma_f32 v[214:215], v[50:51], v[206:207], v[214:215]
	v_pk_fma_f32 v[248:249], v[26:27], v[200:201], v[248:249]
	v_pk_fma_f32 v[216:217], v[50:51], v[208:209], v[216:217]
	v_pk_mul_f32 v[198:199], v[246:247], s[40:41]
	v_pk_mul_f32 v[200:201], v[248:249], s[40:41]
	v_exp_f32_e32 v198, v198
	v_exp_f32_e32 v199, v199
	v_exp_f32_e32 v200, v200
	v_exp_f32_e32 v201, v201
	v_pk_mul_f32 v[214:215], v[214:215], v[246:247]
	v_pk_mul_f32 v[216:217], v[216:217], v[248:249]
	v_pk_add_f32 v[198:199], v[198:199], 1.0 op_sel_hi:[1,0]
	v_pk_add_f32 v[200:201], v[200:201], 1.0 op_sel_hi:[1,0]
	v_rcp_f32_e32 v198, v198
	v_rcp_f32_e32 v199, v199
	v_rcp_f32_e32 v200, v200
	v_rcp_f32_e32 v201, v201
	s_nop 0
	v_pk_mul_f32 v[214:215], v[214:215], v[198:199]
	v_pk_mul_f32 v[216:217], v[216:217], v[200:201]
	v_cvt_pk_bf16_f32 v103, v214, v215
	v_cvt_pk_bf16_f32 v107, v216, v217
	s_add_i32 s38, s42, 1
	s_mul_i32 s39, s38, 0x58000
	s_add_u32 s38, s82, s39
	s_addc_u32 s39, s83, 0
	global_store_dwordx4 v236, v[100:103], s[38:39]
	global_store_dwordx4 v237, v[104:107], s[38:39]
	s_waitcnt vmcnt(12)
	v_lshlrev_b32_e32 v198, 16, v132
	v_and_b32_e32 v199, 0xffff0000, v132
	v_lshlrev_b32_e32 v200, 16, v136
	v_and_b32_e32 v201, 0xffff0000, v136
	v_lshlrev_b32_e32 v202, 16, v140
	v_and_b32_e32 v203, 0xffff0000, v140
	v_lshlrev_b32_e32 v204, 16, v144
	v_and_b32_e32 v205, 0xffff0000, v144
	v_lshlrev_b32_e32 v206, 16, v148
	v_and_b32_e32 v207, 0xffff0000, v148
	v_lshlrev_b32_e32 v208, 16, v152
	v_and_b32_e32 v209, 0xffff0000, v152
	v_lshlrev_b32_e32 v210, 16, v156
	v_and_b32_e32 v211, 0xffff0000, v156
	v_lshlrev_b32_e32 v212, 16, v160
	v_and_b32_e32 v213, 0xffff0000, v160
	v_pk_fma_f32 v[246:247], v[36:37], v[202:203], v[4:5]
	v_pk_fma_f32 v[214:215], v[60:61], v[210:211], v[12:13]
	v_pk_fma_f32 v[248:249], v[36:37], v[204:205], v[4:5]
	v_pk_fma_f32 v[216:217], v[60:61], v[212:213], v[12:13]
	v_pk_fma_f32 v[246:247], v[28:29], v[200:201], v[246:247]
	v_pk_fma_f32 v[214:215], v[52:53], v[208:209], v[214:215]
	v_pk_fma_f32 v[248:249], v[28:29], v[202:203], v[248:249]
	v_pk_fma_f32 v[216:217], v[52:53], v[210:211], v[216:217]
	v_pk_fma_f32 v[246:247], v[20:21], v[198:199], v[246:247]
	v_pk_fma_f32 v[214:215], v[44:45], v[206:207], v[214:215]
	v_pk_fma_f32 v[248:249], v[20:21], v[200:201], v[248:249]
	v_pk_fma_f32 v[216:217], v[44:45], v[208:209], v[216:217]
	v_pk_mul_f32 v[198:199], v[246:247], s[40:41]
	v_pk_mul_f32 v[200:201], v[248:249], s[40:41]
	v_exp_f32_e32 v198, v198
	v_exp_f32_e32 v199, v199
	v_exp_f32_e32 v200, v200
	v_exp_f32_e32 v201, v201
	v_pk_mul_f32 v[214:215], v[214:215], v[246:247]
	v_pk_mul_f32 v[216:217], v[216:217], v[248:249]
	v_pk_add_f32 v[198:199], v[198:199], 1.0 op_sel_hi:[1,0]
	v_pk_add_f32 v[200:201], v[200:201], 1.0 op_sel_hi:[1,0]
	v_rcp_f32_e32 v198, v198
	v_rcp_f32_e32 v199, v199
	v_rcp_f32_e32 v200, v200
	v_rcp_f32_e32 v201, v201
	s_nop 0
	v_pk_mul_f32 v[214:215], v[214:215], v[198:199]
	v_pk_mul_f32 v[216:217], v[216:217], v[200:201]
	v_cvt_pk_bf16_f32 v132, v214, v215
	v_cvt_pk_bf16_f32 v136, v216, v217
	v_lshlrev_b32_e32 v198, 16, v133
	v_and_b32_e32 v199, 0xffff0000, v133
	v_lshlrev_b32_e32 v200, 16, v137
	v_and_b32_e32 v201, 0xffff0000, v137
	v_lshlrev_b32_e32 v202, 16, v141
	v_and_b32_e32 v203, 0xffff0000, v141
	v_lshlrev_b32_e32 v204, 16, v145
	v_and_b32_e32 v205, 0xffff0000, v145
	v_lshlrev_b32_e32 v206, 16, v149
	v_and_b32_e32 v207, 0xffff0000, v149
	v_lshlrev_b32_e32 v208, 16, v153
	v_and_b32_e32 v209, 0xffff0000, v153
	v_lshlrev_b32_e32 v210, 16, v157
	v_and_b32_e32 v211, 0xffff0000, v157
	v_lshlrev_b32_e32 v212, 16, v161
	v_and_b32_e32 v213, 0xffff0000, v161
	v_pk_fma_f32 v[246:247], v[38:39], v[202:203], v[6:7]
	v_pk_fma_f32 v[214:215], v[62:63], v[210:211], v[14:15]
	v_pk_fma_f32 v[248:249], v[38:39], v[204:205], v[6:7]
	v_pk_fma_f32 v[216:217], v[62:63], v[212:213], v[14:15]
	v_pk_fma_f32 v[246:247], v[30:31], v[200:201], v[246:247]
	v_pk_fma_f32 v[214:215], v[54:55], v[208:209], v[214:215]
	v_pk_fma_f32 v[248:249], v[30:31], v[202:203], v[248:249]
	v_pk_fma_f32 v[216:217], v[54:55], v[210:211], v[216:217]
	v_pk_fma_f32 v[246:247], v[22:23], v[198:199], v[246:247]
	v_pk_fma_f32 v[214:215], v[46:47], v[206:207], v[214:215]
	v_pk_fma_f32 v[248:249], v[22:23], v[200:201], v[248:249]
	v_pk_fma_f32 v[216:217], v[46:47], v[208:209], v[216:217]
	v_pk_mul_f32 v[198:199], v[246:247], s[40:41]
	v_pk_mul_f32 v[200:201], v[248:249], s[40:41]
	v_exp_f32_e32 v198, v198
	v_exp_f32_e32 v199, v199
	v_exp_f32_e32 v200, v200
	v_exp_f32_e32 v201, v201
	v_pk_mul_f32 v[214:215], v[214:215], v[246:247]
	v_pk_mul_f32 v[216:217], v[216:217], v[248:249]
	v_pk_add_f32 v[198:199], v[198:199], 1.0 op_sel_hi:[1,0]
	v_pk_add_f32 v[200:201], v[200:201], 1.0 op_sel_hi:[1,0]
	v_rcp_f32_e32 v198, v198
	v_rcp_f32_e32 v199, v199
	v_rcp_f32_e32 v200, v200
	v_rcp_f32_e32 v201, v201
	s_nop 0
	v_pk_mul_f32 v[214:215], v[214:215], v[198:199]
	v_pk_mul_f32 v[216:217], v[216:217], v[200:201]
	v_cvt_pk_bf16_f32 v133, v214, v215
	v_cvt_pk_bf16_f32 v137, v216, v217
	v_lshlrev_b32_e32 v198, 16, v134
	v_and_b32_e32 v199, 0xffff0000, v134
	v_lshlrev_b32_e32 v200, 16, v138
	v_and_b32_e32 v201, 0xffff0000, v138
	v_lshlrev_b32_e32 v202, 16, v142
	v_and_b32_e32 v203, 0xffff0000, v142
	v_lshlrev_b32_e32 v204, 16, v146
	v_and_b32_e32 v205, 0xffff0000, v146
	v_lshlrev_b32_e32 v206, 16, v150
	v_and_b32_e32 v207, 0xffff0000, v150
	v_lshlrev_b32_e32 v208, 16, v154
	v_and_b32_e32 v209, 0xffff0000, v154
	v_lshlrev_b32_e32 v210, 16, v158
	v_and_b32_e32 v211, 0xffff0000, v158
	v_lshlrev_b32_e32 v212, 16, v162
	v_and_b32_e32 v213, 0xffff0000, v162
	v_pk_fma_f32 v[246:247], v[40:41], v[202:203], v[8:9]
	v_pk_fma_f32 v[214:215], v[64:65], v[210:211], v[16:17]
	v_pk_fma_f32 v[248:249], v[40:41], v[204:205], v[8:9]
	v_pk_fma_f32 v[216:217], v[64:65], v[212:213], v[16:17]
	v_pk_fma_f32 v[246:247], v[32:33], v[200:201], v[246:247]
	v_pk_fma_f32 v[214:215], v[56:57], v[208:209], v[214:215]
	v_pk_fma_f32 v[248:249], v[32:33], v[202:203], v[248:249]
	v_pk_fma_f32 v[216:217], v[56:57], v[210:211], v[216:217]
	v_pk_fma_f32 v[246:247], v[24:25], v[198:199], v[246:247]
	v_pk_fma_f32 v[214:215], v[48:49], v[206:207], v[214:215]
	v_pk_fma_f32 v[248:249], v[24:25], v[200:201], v[248:249]
	v_pk_fma_f32 v[216:217], v[48:49], v[208:209], v[216:217]
	v_pk_mul_f32 v[198:199], v[246:247], s[40:41]
	v_pk_mul_f32 v[200:201], v[248:249], s[40:41]
	v_exp_f32_e32 v198, v198
	v_exp_f32_e32 v199, v199
	v_exp_f32_e32 v200, v200
	v_exp_f32_e32 v201, v201
	v_pk_mul_f32 v[214:215], v[214:215], v[246:247]
	v_pk_mul_f32 v[216:217], v[216:217], v[248:249]
	v_pk_add_f32 v[198:199], v[198:199], 1.0 op_sel_hi:[1,0]
	v_pk_add_f32 v[200:201], v[200:201], 1.0 op_sel_hi:[1,0]
	v_rcp_f32_e32 v198, v198
	v_rcp_f32_e32 v199, v199
	v_rcp_f32_e32 v200, v200
	v_rcp_f32_e32 v201, v201
	s_nop 0
	v_pk_mul_f32 v[214:215], v[214:215], v[198:199]
	v_pk_mul_f32 v[216:217], v[216:217], v[200:201]
	v_cvt_pk_bf16_f32 v134, v214, v215
	v_cvt_pk_bf16_f32 v138, v216, v217
	v_lshlrev_b32_e32 v198, 16, v135
	v_and_b32_e32 v199, 0xffff0000, v135
	v_lshlrev_b32_e32 v200, 16, v139
	v_and_b32_e32 v201, 0xffff0000, v139
	v_lshlrev_b32_e32 v202, 16, v143
	v_and_b32_e32 v203, 0xffff0000, v143
	v_lshlrev_b32_e32 v204, 16, v147
	v_and_b32_e32 v205, 0xffff0000, v147
	v_lshlrev_b32_e32 v206, 16, v151
	v_and_b32_e32 v207, 0xffff0000, v151
	v_lshlrev_b32_e32 v208, 16, v155
	v_and_b32_e32 v209, 0xffff0000, v155
	v_lshlrev_b32_e32 v210, 16, v159
	v_and_b32_e32 v211, 0xffff0000, v159
	v_lshlrev_b32_e32 v212, 16, v163
	v_and_b32_e32 v213, 0xffff0000, v163
	v_pk_fma_f32 v[246:247], v[42:43], v[202:203], v[10:11]
	v_pk_fma_f32 v[214:215], v[66:67], v[210:211], v[18:19]
	v_pk_fma_f32 v[248:249], v[42:43], v[204:205], v[10:11]
	v_pk_fma_f32 v[216:217], v[66:67], v[212:213], v[18:19]
	v_pk_fma_f32 v[246:247], v[34:35], v[200:201], v[246:247]
	v_pk_fma_f32 v[214:215], v[58:59], v[208:209], v[214:215]
	v_pk_fma_f32 v[248:249], v[34:35], v[202:203], v[248:249]
	v_pk_fma_f32 v[216:217], v[58:59], v[210:211], v[216:217]
	v_pk_fma_f32 v[246:247], v[26:27], v[198:199], v[246:247]
	v_pk_fma_f32 v[214:215], v[50:51], v[206:207], v[214:215]
	v_pk_fma_f32 v[248:249], v[26:27], v[200:201], v[248:249]
	v_pk_fma_f32 v[216:217], v[50:51], v[208:209], v[216:217]
	v_pk_mul_f32 v[198:199], v[246:247], s[40:41]
	v_pk_mul_f32 v[200:201], v[248:249], s[40:41]
	v_exp_f32_e32 v198, v198
	v_exp_f32_e32 v199, v199
	v_exp_f32_e32 v200, v200
	v_exp_f32_e32 v201, v201
	v_pk_mul_f32 v[214:215], v[214:215], v[246:247]
	v_pk_mul_f32 v[216:217], v[216:217], v[248:249]
	v_pk_add_f32 v[198:199], v[198:199], 1.0 op_sel_hi:[1,0]
	v_pk_add_f32 v[200:201], v[200:201], 1.0 op_sel_hi:[1,0]
	v_rcp_f32_e32 v198, v198
	v_rcp_f32_e32 v199, v199
	v_rcp_f32_e32 v200, v200
	v_rcp_f32_e32 v201, v201
	s_nop 0
	v_pk_mul_f32 v[214:215], v[214:215], v[198:199]
	v_pk_mul_f32 v[216:217], v[216:217], v[200:201]
	v_cvt_pk_bf16_f32 v135, v214, v215
	v_cvt_pk_bf16_f32 v139, v216, v217
	s_add_i32 s38, s42, 2
	s_mul_i32 s39, s38, 0x58000
	s_add_u32 s38, s82, s39
	s_addc_u32 s39, s83, 0
	global_store_dwordx4 v236, v[132:135], s[38:39]
	global_store_dwordx4 v237, v[136:139], s[38:39]
	s_waitcnt vmcnt(6)
	v_lshlrev_b32_e32 v198, 16, v164
	v_and_b32_e32 v199, 0xffff0000, v164
	v_lshlrev_b32_e32 v200, 16, v168
	v_and_b32_e32 v201, 0xffff0000, v168
	v_lshlrev_b32_e32 v202, 16, v172
	v_and_b32_e32 v203, 0xffff0000, v172
	v_lshlrev_b32_e32 v204, 16, v176
	v_and_b32_e32 v205, 0xffff0000, v176
	v_lshlrev_b32_e32 v206, 16, v180
	v_and_b32_e32 v207, 0xffff0000, v180
	v_lshlrev_b32_e32 v208, 16, v184
	v_and_b32_e32 v209, 0xffff0000, v184
	v_lshlrev_b32_e32 v210, 16, v188
	v_and_b32_e32 v211, 0xffff0000, v188
	v_lshlrev_b32_e32 v212, 16, v192
	v_and_b32_e32 v213, 0xffff0000, v192
	v_pk_fma_f32 v[246:247], v[36:37], v[202:203], v[4:5]
	v_pk_fma_f32 v[214:215], v[60:61], v[210:211], v[12:13]
	v_pk_fma_f32 v[248:249], v[36:37], v[204:205], v[4:5]
	v_pk_fma_f32 v[216:217], v[60:61], v[212:213], v[12:13]
	v_pk_fma_f32 v[246:247], v[28:29], v[200:201], v[246:247]
	v_pk_fma_f32 v[214:215], v[52:53], v[208:209], v[214:215]
	v_pk_fma_f32 v[248:249], v[28:29], v[202:203], v[248:249]
	v_pk_fma_f32 v[216:217], v[52:53], v[210:211], v[216:217]
	v_pk_fma_f32 v[246:247], v[20:21], v[198:199], v[246:247]
	v_pk_fma_f32 v[214:215], v[44:45], v[206:207], v[214:215]
	v_pk_fma_f32 v[248:249], v[20:21], v[200:201], v[248:249]
	v_pk_fma_f32 v[216:217], v[44:45], v[208:209], v[216:217]
	v_pk_mul_f32 v[198:199], v[246:247], s[40:41]
	v_pk_mul_f32 v[200:201], v[248:249], s[40:41]
	v_exp_f32_e32 v198, v198
	v_exp_f32_e32 v199, v199
	v_exp_f32_e32 v200, v200
	v_exp_f32_e32 v201, v201
	v_pk_mul_f32 v[214:215], v[214:215], v[246:247]
	v_pk_mul_f32 v[216:217], v[216:217], v[248:249]
	v_pk_add_f32 v[198:199], v[198:199], 1.0 op_sel_hi:[1,0]
	v_pk_add_f32 v[200:201], v[200:201], 1.0 op_sel_hi:[1,0]
	v_rcp_f32_e32 v198, v198
	v_rcp_f32_e32 v199, v199
	v_rcp_f32_e32 v200, v200
	v_rcp_f32_e32 v201, v201
	s_nop 0
	v_pk_mul_f32 v[214:215], v[214:215], v[198:199]
	v_pk_mul_f32 v[216:217], v[216:217], v[200:201]
	v_cvt_pk_bf16_f32 v164, v214, v215
	v_cvt_pk_bf16_f32 v168, v216, v217
	v_lshlrev_b32_e32 v198, 16, v165
	v_and_b32_e32 v199, 0xffff0000, v165
	v_lshlrev_b32_e32 v200, 16, v169
	v_and_b32_e32 v201, 0xffff0000, v169
	v_lshlrev_b32_e32 v202, 16, v173
	v_and_b32_e32 v203, 0xffff0000, v173
	v_lshlrev_b32_e32 v204, 16, v177
	v_and_b32_e32 v205, 0xffff0000, v177
	v_lshlrev_b32_e32 v206, 16, v181
	v_and_b32_e32 v207, 0xffff0000, v181
	v_lshlrev_b32_e32 v208, 16, v185
	v_and_b32_e32 v209, 0xffff0000, v185
	v_lshlrev_b32_e32 v210, 16, v189
	v_and_b32_e32 v211, 0xffff0000, v189
	v_lshlrev_b32_e32 v212, 16, v193
	v_and_b32_e32 v213, 0xffff0000, v193
	v_pk_fma_f32 v[246:247], v[38:39], v[202:203], v[6:7]
	v_pk_fma_f32 v[214:215], v[62:63], v[210:211], v[14:15]
	v_pk_fma_f32 v[248:249], v[38:39], v[204:205], v[6:7]
	v_pk_fma_f32 v[216:217], v[62:63], v[212:213], v[14:15]
	v_pk_fma_f32 v[246:247], v[30:31], v[200:201], v[246:247]
	v_pk_fma_f32 v[214:215], v[54:55], v[208:209], v[214:215]
	v_pk_fma_f32 v[248:249], v[30:31], v[202:203], v[248:249]
	v_pk_fma_f32 v[216:217], v[54:55], v[210:211], v[216:217]
	v_pk_fma_f32 v[246:247], v[22:23], v[198:199], v[246:247]
	v_pk_fma_f32 v[214:215], v[46:47], v[206:207], v[214:215]
	v_pk_fma_f32 v[248:249], v[22:23], v[200:201], v[248:249]
	v_pk_fma_f32 v[216:217], v[46:47], v[208:209], v[216:217]
	v_pk_mul_f32 v[198:199], v[246:247], s[40:41]
	v_pk_mul_f32 v[200:201], v[248:249], s[40:41]
	v_exp_f32_e32 v198, v198
	v_exp_f32_e32 v199, v199
	v_exp_f32_e32 v200, v200
	v_exp_f32_e32 v201, v201
	v_pk_mul_f32 v[214:215], v[214:215], v[246:247]
	v_pk_mul_f32 v[216:217], v[216:217], v[248:249]
	v_pk_add_f32 v[198:199], v[198:199], 1.0 op_sel_hi:[1,0]
	v_pk_add_f32 v[200:201], v[200:201], 1.0 op_sel_hi:[1,0]
	v_rcp_f32_e32 v198, v198
	v_rcp_f32_e32 v199, v199
	v_rcp_f32_e32 v200, v200
	v_rcp_f32_e32 v201, v201
	s_nop 0
	v_pk_mul_f32 v[214:215], v[214:215], v[198:199]
	v_pk_mul_f32 v[216:217], v[216:217], v[200:201]
	v_cvt_pk_bf16_f32 v165, v214, v215
	v_cvt_pk_bf16_f32 v169, v216, v217
	v_lshlrev_b32_e32 v198, 16, v166
	v_and_b32_e32 v199, 0xffff0000, v166
	v_lshlrev_b32_e32 v200, 16, v170
	v_and_b32_e32 v201, 0xffff0000, v170
	v_lshlrev_b32_e32 v202, 16, v174
	v_and_b32_e32 v203, 0xffff0000, v174
	v_lshlrev_b32_e32 v204, 16, v178
	v_and_b32_e32 v205, 0xffff0000, v178
	v_lshlrev_b32_e32 v206, 16, v182
	v_and_b32_e32 v207, 0xffff0000, v182
	v_lshlrev_b32_e32 v208, 16, v186
	v_and_b32_e32 v209, 0xffff0000, v186
	v_lshlrev_b32_e32 v210, 16, v190
	v_and_b32_e32 v211, 0xffff0000, v190
	v_lshlrev_b32_e32 v212, 16, v194
	v_and_b32_e32 v213, 0xffff0000, v194
	v_pk_fma_f32 v[246:247], v[40:41], v[202:203], v[8:9]
	v_pk_fma_f32 v[214:215], v[64:65], v[210:211], v[16:17]
	v_pk_fma_f32 v[248:249], v[40:41], v[204:205], v[8:9]
	v_pk_fma_f32 v[216:217], v[64:65], v[212:213], v[16:17]
	v_pk_fma_f32 v[246:247], v[32:33], v[200:201], v[246:247]
	v_pk_fma_f32 v[214:215], v[56:57], v[208:209], v[214:215]
	v_pk_fma_f32 v[248:249], v[32:33], v[202:203], v[248:249]
	v_pk_fma_f32 v[216:217], v[56:57], v[210:211], v[216:217]
	v_pk_fma_f32 v[246:247], v[24:25], v[198:199], v[246:247]
	v_pk_fma_f32 v[214:215], v[48:49], v[206:207], v[214:215]
	v_pk_fma_f32 v[248:249], v[24:25], v[200:201], v[248:249]
	v_pk_fma_f32 v[216:217], v[48:49], v[208:209], v[216:217]
	v_pk_mul_f32 v[198:199], v[246:247], s[40:41]
	v_pk_mul_f32 v[200:201], v[248:249], s[40:41]
	v_exp_f32_e32 v198, v198
	v_exp_f32_e32 v199, v199
	v_exp_f32_e32 v200, v200
	v_exp_f32_e32 v201, v201
	v_pk_mul_f32 v[214:215], v[214:215], v[246:247]
	v_pk_mul_f32 v[216:217], v[216:217], v[248:249]
	v_pk_add_f32 v[198:199], v[198:199], 1.0 op_sel_hi:[1,0]
	v_pk_add_f32 v[200:201], v[200:201], 1.0 op_sel_hi:[1,0]
	v_rcp_f32_e32 v198, v198
	v_rcp_f32_e32 v199, v199
	v_rcp_f32_e32 v200, v200
	v_rcp_f32_e32 v201, v201
	s_nop 0
	v_pk_mul_f32 v[214:215], v[214:215], v[198:199]
	v_pk_mul_f32 v[216:217], v[216:217], v[200:201]
	v_cvt_pk_bf16_f32 v166, v214, v215
	v_cvt_pk_bf16_f32 v170, v216, v217
	v_lshlrev_b32_e32 v198, 16, v167
	v_and_b32_e32 v199, 0xffff0000, v167
	v_lshlrev_b32_e32 v200, 16, v171
	v_and_b32_e32 v201, 0xffff0000, v171
	v_lshlrev_b32_e32 v202, 16, v175
	v_and_b32_e32 v203, 0xffff0000, v175
	v_lshlrev_b32_e32 v204, 16, v179
	v_and_b32_e32 v205, 0xffff0000, v179
	v_lshlrev_b32_e32 v206, 16, v183
	v_and_b32_e32 v207, 0xffff0000, v183
	v_lshlrev_b32_e32 v208, 16, v187
	v_and_b32_e32 v209, 0xffff0000, v187
	v_lshlrev_b32_e32 v210, 16, v191
	v_and_b32_e32 v211, 0xffff0000, v191
	v_lshlrev_b32_e32 v212, 16, v195
	v_and_b32_e32 v213, 0xffff0000, v195
	v_pk_fma_f32 v[246:247], v[42:43], v[202:203], v[10:11]
	v_pk_fma_f32 v[214:215], v[66:67], v[210:211], v[18:19]
	v_pk_fma_f32 v[248:249], v[42:43], v[204:205], v[10:11]
	v_pk_fma_f32 v[216:217], v[66:67], v[212:213], v[18:19]
	v_pk_fma_f32 v[246:247], v[34:35], v[200:201], v[246:247]
	v_pk_fma_f32 v[214:215], v[58:59], v[208:209], v[214:215]
	v_pk_fma_f32 v[248:249], v[34:35], v[202:203], v[248:249]
	v_pk_fma_f32 v[216:217], v[58:59], v[210:211], v[216:217]
	v_pk_fma_f32 v[246:247], v[26:27], v[198:199], v[246:247]
	v_pk_fma_f32 v[214:215], v[50:51], v[206:207], v[214:215]
	v_pk_fma_f32 v[248:249], v[26:27], v[200:201], v[248:249]
	v_pk_fma_f32 v[216:217], v[50:51], v[208:209], v[216:217]
	v_pk_mul_f32 v[198:199], v[246:247], s[40:41]
	v_pk_mul_f32 v[200:201], v[248:249], s[40:41]
	v_exp_f32_e32 v198, v198
	v_exp_f32_e32 v199, v199
	v_exp_f32_e32 v200, v200
	v_exp_f32_e32 v201, v201
	v_pk_mul_f32 v[214:215], v[214:215], v[246:247]
	v_pk_mul_f32 v[216:217], v[216:217], v[248:249]
	v_pk_add_f32 v[198:199], v[198:199], 1.0 op_sel_hi:[1,0]
	v_pk_add_f32 v[200:201], v[200:201], 1.0 op_sel_hi:[1,0]
	v_rcp_f32_e32 v198, v198
	v_rcp_f32_e32 v199, v199
	v_rcp_f32_e32 v200, v200
	v_rcp_f32_e32 v201, v201
	s_nop 0
	v_pk_mul_f32 v[214:215], v[214:215], v[198:199]
	v_pk_mul_f32 v[216:217], v[216:217], v[200:201]
	v_cvt_pk_bf16_f32 v167, v214, v215
	v_cvt_pk_bf16_f32 v171, v216, v217
	s_add_i32 s38, s42, 3
	s_mul_i32 s39, s38, 0x58000
	s_add_u32 s38, s82, s39
	s_addc_u32 s39, s83, 0
	global_store_dwordx4 v236, v[164:167], s[38:39]
	global_store_dwordx4 v237, v[168:171], s[38:39]
	s_branch .LBB0_29

.LBB0_410:
	s_or_b64 exec, exec, s[0:1]
	s_bfe_u32 s0, s22, 0x20006
	s_lshl_b32 s1, s23, 2
	s_or_b32 s23, s0, s1
	s_add_i32 s0, s23, 1
	v_and_b32_e32 v55, 15, v1
	v_bfe_u32 v0, v1, 4, 2
	v_cvt_f32_ubyte0_e32 v1, s0
	v_mul_f32_e32 v2, -0.5, v1
	s_mov_b32 s0, 0xc2fc0000
	v_cmp_gt_f32_e32 vcc, s0, v2
	v_mov_b32_e32 v2, 0x42800000
	s_and_b64 s[0:1], vcc, exec
	v_cndmask_b32_e32 v2, 0, v2, vcc
	v_fmac_f32_e32 v2, -0.5, v1
	v_exp_f32_e32 v1, v2
	s_cselect_b32 s0, 0xffffffc0, 0
	s_waitcnt lgkmcnt(0)
	s_barrier
	v_ldexp_f32 v49, v1, s0
	s_lshl_b32 s0, s23, 2
	v_mov_b32_e32 v1, s0
	v_readlane_b32 s0, v252, 56
	v_readlane_b32 s6, v252, 62
	v_readlane_b32 s7, v252, 63
	s_ashr_i32 s31, s22, 8
	s_cmp_lg_u32 s20, 0
	s_cselect_b64 s[82:83], -1, 0
	s_lshl_b32 s0, s23, 6
	s_nop 0
	global_load_dword v57, v1, s[6:7]
	s_cmp_lt_u32 s21, 2
	s_cselect_b64 s[74:75], -1, 0
	s_lshl_b32 s37, s31, 4
	v_lshlrev_b32_e32 v50, 3, v0
	v_lshl_add_u32 v52, v0, 4, 0
	v_lshlrev_b32_e32 v54, 2, v0
	v_and_or_b32 v0, s37, 16, v55
	v_or_b32_e32 v0, 0x80, v0
	v_readlane_b32 s2, v252, 58
	v_readlane_b32 s3, v252, 59
	v_sub_u32_e32 v1, v0, v54
	v_cvt_f32_ubyte0_e32 v0, v1
	s_mov_b32 s2, 2.0
	v_mul_f32_e32 v0, v49, v0
	v_mov_b32_e32 v2, v49
	s_mov_b32 s3, 0x40400000
	v_pk_fma_f32 v[60:61], v[2:3], s[2:3], v[0:1] op_sel_hi:[0,1,0] neg_lo:[0,0,1] neg_hi:[0,0,1]
	s_mov_b32 s2, 0x41800000
	s_mov_b32 s3, 0x41880000
	v_pk_fma_f32 v[62:63], v[2:3], s[2:3], v[0:1] op_sel_hi:[0,1,0] neg_lo:[0,0,1] neg_hi:[0,0,1]
	s_mov_b32 s2, 0x41900000
	s_mov_b32 s3, 0x41980000
	v_pk_fma_f32 v[64:65], v[2:3], s[2:3], v[0:1] op_sel_hi:[0,1,0] neg_lo:[0,0,1] neg_hi:[0,0,1]
	s_mov_b32 s2, 0x42000000
	s_mov_b32 s3, 0x42040000
	v_pk_fma_f32 v[66:67], v[2:3], s[2:3], v[0:1] op_sel_hi:[0,1,0] neg_lo:[0,0,1] neg_hi:[0,0,1]
	s_mov_b32 s2, 0x42080000
	s_mov_b32 s3, 0x420c0000
	v_pk_fma_f32 v[68:69], v[2:3], s[2:3], v[0:1] op_sel_hi:[0,1,0] neg_lo:[0,0,1] neg_hi:[0,0,1]
	s_mov_b32 s2, 0x42400000
	s_mov_b32 s3, 0x42440000
	v_pk_fma_f32 v[70:71], v[2:3], s[2:3], v[0:1] op_sel_hi:[0,1,0] neg_lo:[0,0,1] neg_hi:[0,0,1]
	s_mov_b32 s2, 0x42480000
	s_mov_b32 s3, 0x424c0000
	v_pk_fma_f32 v[72:73], v[2:3], s[2:3], v[0:1] op_sel_hi:[0,1,0] neg_lo:[0,0,1] neg_hi:[0,0,1]
	s_mov_b32 s2, 0x42800000
	s_mov_b32 s3, 0x42820000
	v_pk_fma_f32 v[74:75], v[2:3], s[2:3], v[0:1] op_sel_hi:[0,1,0] neg_lo:[0,0,1] neg_hi:[0,0,1]
	s_mov_b32 s2, 0x42840000
	s_mov_b32 s3, 0x42860000
	v_pk_fma_f32 v[76:77], v[2:3], s[2:3], v[0:1] op_sel_hi:[0,1,0] neg_lo:[0,0,1] neg_hi:[0,0,1]
	s_mov_b32 s2, 0x42a00000
	s_mov_b32 s3, 0x42a20000
	v_pk_fma_f32 v[78:79], v[2:3], s[2:3], v[0:1] op_sel_hi:[0,1,0] neg_lo:[0,0,1] neg_hi:[0,0,1]
	s_mov_b32 s2, 0x42a40000
	s_mov_b32 s3, 0x42a60000
	v_pk_fma_f32 v[80:81], v[2:3], s[2:3], v[0:1] op_sel_hi:[0,1,0] neg_lo:[0,0,1] neg_hi:[0,0,1]
	s_mov_b32 s2, 0x42c00000
	s_mov_b32 s3, 0x42c20000
	v_pk_fma_f32 v[82:83], v[2:3], s[2:3], v[0:1] op_sel_hi:[0,1,0] neg_lo:[0,0,1] neg_hi:[0,0,1]
	s_mov_b32 s2, 0x42c40000
	s_mov_b32 s3, 0x42c60000
	v_pk_fma_f32 v[84:85], v[2:3], s[2:3], v[0:1] op_sel_hi:[0,1,0] neg_lo:[0,0,1] neg_hi:[0,0,1]
	s_mov_b32 s2, 0x42e00000
	s_mov_b32 s3, 0x42e20000
	v_pk_fma_f32 v[86:87], v[2:3], s[2:3], v[0:1] op_sel_hi:[0,1,0] neg_lo:[0,0,1] neg_hi:[0,0,1]
	s_mov_b32 s2, 0x42e40000
	v_add_u32_e32 v5, -2, v1
	s_mov_b32 s3, 0x42e60000
	v_cmp_gt_u32_e64 s[44:45], s69, v5
	v_add_u32_e32 v5, -16, v1
	v_pk_fma_f32 v[88:89], v[2:3], s[2:3], v[0:1] op_sel_hi:[0,1,0] neg_lo:[0,0,1] neg_hi:[0,0,1]
	s_mov_b32 s2, 0x43010000
	v_readlane_b32 s1, v252, 57
	v_add_u32_e32 v6, -3, v1
	v_cmp_gt_u32_e64 s[48:49], s69, v5
	v_subrev_u32_e32 v5, 18, v1
	s_mov_b32 s3, 0x43020000
	s_movk_i32 s1, 0x81
	v_cmp_gt_u32_e64 s[42:43], s69, v6
	v_subrev_u32_e32 v6, 17, v1
	v_cmp_gt_u32_e64 s[52:53], s69, v5
	v_add_u32_e32 v5, 0xffffff7f, v1
	v_pk_fma_f32 v[90:91], v[2:3], s[2:3], v[0:1] op_sel_hi:[0,1,0] neg_lo:[0,0,1] neg_hi:[0,0,1]
	s_mov_b32 s2, 0x43100000
	v_cmp_gt_u32_e64 s[40:41], s1, v1
	v_cmp_gt_u32_e64 s[46:47], s69, v6
	v_subrev_u32_e32 v6, 19, v1
	s_mov_b32 s1, 0x43000000
	v_cmp_gt_u32_e64 s[56:57], s69, v5
	v_add_u32_e32 v5, 0xffffff7d, v1
	s_mov_b32 s3, 0x43110000
	v_mul_f32_e32 v48, 0, v49
	v_cmp_gt_u32_e64 s[50:51], s69, v6
	v_fma_f32 v125, v49, s1, -v0
	v_add_u32_e32 v6, 0xffffff7e, v1
	v_cmp_gt_u32_e64 s[58:59], s69, v5
	s_mov_b32 s1, 0x43030000
	v_add_u32_e32 v5, 0xffffff70, v1
	v_pk_fma_f32 v[92:93], v[2:3], s[2:3], v[0:1] op_sel_hi:[0,1,0] neg_lo:[0,0,1] neg_hi:[0,0,1]
	s_mov_b32 s2, 0x43120000
	v_cmp_gt_u32_e64 s[38:39], s69, v1
	v_pk_add_f32 v[58:59], v[48:49], v[0:1] op_sel_hi:[1,0] neg_lo:[0,1] neg_hi:[0,1]
	v_cmp_gt_u32_e64 s[54:55], s69, v6
	v_fma_f32 v126, v49, s1, -v0
	v_add_u32_e32 v6, 0xffffff6f, v1
	v_cmp_gt_u32_e64 s[62:63], s69, v5
	v_add_u32_e32 v5, 0xffffff6e, v1
	v_add_u32_e32 v1, 0xffffff6d, v1
	s_mov_b32 s3, 0x43130000
	v_readlane_b32 s1, v254, 37
	v_pk_fma_f32 v[94:95], v[2:3], s[2:3], v[0:1] op_sel_hi:[0,1,0] neg_lo:[0,0,1] neg_hi:[0,0,1]
	s_sub_i32 s36, 0x8f, s70
	v_mov_b32_e32 v0, s1
	s_movk_i32 s1, 0x230
	v_mul_u32_u24_e32 v4, 0x90, v55
	v_mad_u32_u24 v0, v55, s1, v0
	v_or_b32_e32 v131, s37, v55
	s_add_i32 s70, s70, s37
	s_mov_b32 s30, 0
	v_sub_u32_e32 v124, v52, v50
	v_or_b32_e32 v51, 3, v54
	v_or_b32_e32 v56, 2, v54
	v_cmp_gt_u32_e64 s[60:61], s69, v6
	v_mul_u32_u24_e32 v127, 0x230, v55
	v_mad_u32_u24 v128, v55, s1, 0
	v_add_u32_e32 v129, 0x6900, v0
	v_xor_b32_e32 v130, 0xffffffed, v54
	v_xor_b32_e32 v132, 0xffffffee, v54
	v_xor_b32_e32 v133, 0xffffffef, v54
	v_sub_u32_e32 v134, -16, v54
	v_xor_b32_e32 v135, -3, v54
	v_xor_b32_e32 v136, -2, v54
	v_not_b32_e32 v137, v54
	v_sub_u32_e32 v138, 0, v54
	v_xor_b32_e32 v139, 13, v54
	v_xor_b32_e32 v140, 14, v54
	v_xor_b32_e32 v141, 15, v54
	v_sub_u32_e32 v142, 16, v54
	v_xor_b32_e32 v143, 29, v54
	v_xor_b32_e32 v144, 30, v54
	v_xor_b32_e32 v145, 31, v54
	v_sub_u32_e32 v146, 32, v54
	v_xor_b32_e32 v147, 45, v54
	v_xor_b32_e32 v148, 46, v54
	v_xor_b32_e32 v149, 47, v54
	v_sub_u32_e32 v150, 48, v54
	v_xor_b32_e32 v151, 61, v54
	v_xor_b32_e32 v152, 62, v54
	v_xor_b32_e32 v153, 63, v54
	v_sub_u32_e32 v154, 64, v54
	v_xor_b32_e32 v155, 0x4d, v54
	v_xor_b32_e32 v156, 0x4e, v54
	v_xor_b32_e32 v157, 0x4f, v54
	v_sub_u32_e32 v158, 0x50, v54
	v_xor_b32_e32 v159, 0x5d, v54
	v_xor_b32_e32 v160, 0x5e, v54
	v_xor_b32_e32 v161, 0x5f, v54
	v_sub_u32_e32 v162, 0x60, v54
	v_sub_u32_e32 v163, v131, v54
	v_xor_b32_e32 v164, 0x7d, v54
	v_xor_b32_e32 v165, 0x7e, v54
	v_xor_b32_e32 v166, 0x7f, v54
	v_sub_u32_e32 v167, 0x80, v54
	v_add_u32_e32 v168, s70, v55
	v_add_u32_e32 v169, v52, v4
	s_lshl_b32 s72, s0, 1
	v_cmp_gt_u32_e64 s[64:65], s69, v1
	v_cmp_gt_u32_e64 s[66:67], s69, v5
	v_readlane_b32 s4, v252, 60
	v_readlane_b32 s5, v252, 61
	v_readlane_b32 s8, v253, 0
	v_readlane_b32 s9, v253, 1
	v_readlane_b32 s10, v253, 2
	v_readlane_b32 s11, v253, 3
	v_readlane_b32 s12, v253, 4
	v_readlane_b32 s13, v253, 5
	v_readlane_b32 s14, v253, 6
	v_readlane_b32 s15, v253, 7
	v_lshlrev_b32_e32 v222, 1, v50
	v_add_u32_e32 v222, s72, v222
	v_add_u32_e32 v222, 0x4002800, v222
	v_cmp_lt_i32_e64 s[98:99], 15, v168
	s_nop 1
	v_cndmask_b32_e64 v249, v229, v53, s[98:99]
	v_add_u32_e32 v248, v168, v249
	v_mad_u32_u24 v248, v248, s29, v222
	global_load_dwordx4 v[240:243], v248, s[92:93]
	global_load_dwordx4 v[244:247], v248, s[92:93] offset:64
	s_waitcnt vmcnt(0)
	s_branch .LBB0_413
.Lattn_skip:
	v_add_u32_e32 v248, s30, v168
	v_add_u32_e32 v248, 32, v248
	v_cmp_lt_i32_e64 s[98:99], 15, v248
	s_nop 1
	v_cndmask_b32_e64 v249, v229, v53, s[98:99]
	v_add_u32_e32 v248, v248, v249
	v_mad_u32_u24 v248, v248, s29, v222
	global_load_dwordx4 v[240:243], v248, s[92:93]
	global_load_dwordx4 v[244:247], v248, s[92:93] offset:64
	s_waitcnt vmcnt(0)
	s_branch .LBB0_412

.LBB0_413:
	s_add_i32 s20, s70, s30
	s_cmpk_gt_i32 s20, 0x100f
	s_cselect_b64 s[0:1], -1, 0
	s_cmp_lt_i32 s20, 16
	s_cselect_b64 s[20:21], -1, 0
	s_and_b64 s[20:21], s[82:83], s[20:21]
	s_or_b64 s[0:1], s[0:1], s[20:21]
	s_and_b64 vcc, exec, s[0:1]
	s_cbranch_vccnz .Lattn_skip
	v_add_u32_e32 v120, s30, v168
	v_cmp_lt_i32_e32 vcc, 15, v120
	s_and_b32 s78, s31, -2
	s_lshl_b32 s85, s78, 4
	v_cndmask_b32_e32 v0, v229, v53, vcc
	v_add_u32_e32 v2, v120, v0
	v_mov_b64_e32 v[0:1], s[92:93]
	v_mad_i64_i32 v[0:1], s[0:1], v2, s29, v[0:1]
	v_lshl_add_u64 v[0:1], v[0:1], 0, s[72:73]
	s_mov_b64 s[0:1], 0x4002800
	v_lshl_add_u64 v[96:97], v[0:1], 0, s[0:1]
	v_lshlrev_b32_e32 v2, 1, v50
	v_lshl_add_u64 v[0:1], v[96:97], 0, v[2:3]
	s_add_i32 s20, s37, s30
	v_or_b32_e32 v0, s85, v55
	v_mad_u64_u32 v[0:1], s[0:1], v0, s71, v[52:53]
	s_or_b32 s81, s20, 16
	ds_read_b128 v[4:7], v0
	ds_read_b128 v[8:11], v0 offset:64
	v_or_b32_e32 v0, s81, v55
	v_mad_u64_u32 v[0:1], s[0:1], v0, s71, v[52:53]
	s_add_i32 s27, s85, 32
	ds_read_b128 v[12:15], v0
	ds_read_b128 v[16:19], v0 offset:64
	v_or_b32_e32 v0, s27, v55
	v_mad_u64_u32 v[0:1], s[0:1], v0, s71, v[52:53]
	s_add_i32 s26, s85, 48
	ds_read_b128 v[20:23], v0
	ds_read_b128 v[24:27], v0 offset:64
	v_or_b32_e32 v0, s26, v55
	v_mad_u64_u32 v[0:1], s[0:1], v0, s71, v[52:53]
	s_add_i32 s25, s85, 64
	ds_read_b128 v[28:31], v0
	ds_read_b128 v[98:101], v0 offset:64
	v_or_b32_e32 v0, s25, v55
	v_mad_u64_u32 v[0:1], s[0:1], v0, s71, v[52:53]
	s_add_i32 s24, s85, 0x50
	ds_read_b128 v[102:105], v0
	ds_read_b128 v[106:109], v0 offset:64
	v_or_b32_e32 v0, s24, v55
	v_mad_u64_u32 v[0:1], s[0:1], v0, s71, v[52:53]
	s_add_i32 s23, s85, 0x60
	ds_read_b128 v[110:113], v0
	ds_read_b128 v[114:117], v0 offset:64
	v_or_b32_e32 v0, s23, v55
	v_mad_u64_u32 v[0:1], s[0:1], v0, s71, v[52:53]
	s_add_i32 s22, s85, 0x70
	ds_read_b128 v[170:173], v0
	ds_read_b128 v[174:177], v0 offset:64
	v_or_b32_e32 v0, s22, v55
	v_mad_u64_u32 v[0:1], s[0:1], v0, s71, v[52:53]
	s_add_i32 s21, s85, 0x80
	ds_read_b128 v[178:181], v0
	ds_read_b128 v[182:185], v0 offset:64
	v_or_b32_e32 v0, s21, v55
	v_mad_u64_u32 v[0:1], s[0:1], v0, s71, v[52:53]
	s_add_i32 s20, s85, 0x90
	ds_read_b128 v[186:189], v0
	ds_read_b128 v[190:193], v0 offset:64
	v_or_b32_e32 v0, s20, v55
	v_mad_u64_u32 v[0:1], s[0:1], v0, s71, v[52:53]
	ds_read_b128 v[206:209], v0
	ds_read_b128 v[210:213], v0 offset:64
	ds_read_b128 v[214:217], v169 offset:36864
	ds_read_b128 v[236:239], v169 offset:36928
	s_waitcnt vmcnt(4) lgkmcnt(14)
	v_mfma_f32_16x16x32_bf16 v[4:7], v[4:7], v[240:243], 0
	s_mov_b64 s[0:1], -1
	s_andn2_b64 vcc, exec, s[74:75]
	v_mfma_f32_16x16x32_bf16 v[44:47], v[8:11], v[244:247], v[4:7]
	v_mfma_f32_16x16x32_bf16 v[4:7], v[12:15], v[240:243], 0
	v_mfma_f32_16x16x32_bf16 v[40:43], v[16:19], v[244:247], v[4:7]
	v_mfma_f32_16x16x32_bf16 v[4:7], v[20:23], v[240:243], 0
	v_mfma_f32_16x16x32_bf16 v[36:39], v[24:27], v[244:247], v[4:7]
	v_mfma_f32_16x16x32_bf16 v[4:7], v[28:31], v[240:243], 0
	v_mfma_f32_16x16x32_bf16 v[28:31], v[98:101], v[244:247], v[4:7]
	s_waitcnt lgkmcnt(13)
	v_mfma_f32_16x16x32_bf16 v[4:7], v[102:105], v[240:243], 0
	s_waitcnt lgkmcnt(12)
	v_mfma_f32_16x16x32_bf16 v[24:27], v[106:109], v[244:247], v[4:7]
	s_waitcnt lgkmcnt(11)
	v_mfma_f32_16x16x32_bf16 v[4:7], v[110:113], v[240:243], 0
	s_waitcnt lgkmcnt(10)
	v_mfma_f32_16x16x32_bf16 v[20:23], v[114:117], v[244:247], v[4:7]
	s_waitcnt lgkmcnt(9)
	v_mfma_f32_16x16x32_bf16 v[4:7], v[170:173], v[240:243], 0
	s_waitcnt lgkmcnt(8)
	v_mfma_f32_16x16x32_bf16 v[16:19], v[174:177], v[244:247], v[4:7]
	s_waitcnt lgkmcnt(7)
	v_mfma_f32_16x16x32_bf16 v[4:7], v[178:181], v[240:243], 0
	v_or_b32_e32 v179, s27, v54
	v_or_b32_e32 v180, s25, v54
	v_or_b32_e32 v181, s23, v54
	s_waitcnt lgkmcnt(6)
	v_mfma_f32_16x16x32_bf16 v[12:15], v[182:185], v[244:247], v[4:7]
	v_or_b32_e32 v182, s21, v54
	s_waitcnt lgkmcnt(5)
	v_mfma_f32_16x16x32_bf16 v[4:7], v[186:189], v[240:243], 0
	s_waitcnt lgkmcnt(4)
	v_mfma_f32_16x16x32_bf16 v[8:11], v[190:193], v[244:247], v[4:7]
	s_waitcnt lgkmcnt(3)
	v_mfma_f32_16x16x32_bf16 v[4:7], v[206:209], v[240:243], 0
	s_waitcnt lgkmcnt(1)
	v_mfma_f32_16x16x32_bf16 v[32:35], v[214:217], v[240:243], 0
	v_mfma_f32_16x16x32_bf16 v[4:7], v[210:213], v[244:247], v[4:7]
	s_waitcnt lgkmcnt(0)
	v_mfma_f32_16x16x32_bf16 v[32:35], v[236:239], v[244:247], v[32:35]
	v_add_u32_e32 v248, s30, v168
	v_add_u32_e32 v248, 32, v248
	v_cmp_lt_i32_e64 s[98:99], 15, v248
	s_nop 1
	v_cndmask_b32_e64 v249, v229, v53, s[98:99]
	v_add_u32_e32 v248, v248, v249
	v_mad_u32_u24 v248, v248, s29, v222
	global_load_dwordx4 v[240:243], v248, s[92:93]
	global_load_dwordx4 v[244:247], v248, s[92:93] offset:64
	s_cbranch_vccnz .LBB0_416
	s_lshl_b32 s0, s31, 4
	s_andn2_b32 s0, s0, 31
	v_subrev_u32_e32 v0, s0, v167
	v_add_u32_e32 v191, s30, v131
	v_add_u32_e32 v171, v191, v0
	v_cvt_f32_i32_e32 v201, v171
	v_subrev_u32_e32 v173, s0, v166
	v_mov_b32_e32 v48, v44
	v_cmp_gt_u32_e32 vcc, s69, v171
	v_add_u32_e32 v171, v191, v173
	v_pk_mul_f32 v[0:1], v[48:49], v[200:201]
	v_cvt_f32_i32_e32 v201, v171
	v_or_b32_e32 v175, s85, v54
	v_subrev_u32_e32 v121, s0, v130
	v_subrev_u32_e32 v122, s0, v132
	v_subrev_u32_e32 v123, s0, v133
	v_subrev_u32_e32 v189, s0, v134
	v_subrev_u32_e32 v187, s0, v135
	v_subrev_u32_e32 v188, s0, v136
	v_subrev_u32_e32 v185, s0, v137
	v_subrev_u32_e32 v172, s0, v138
	v_subrev_u32_e32 v118, s0, v139
	v_subrev_u32_e32 v119, s0, v140
	v_subrev_u32_e32 v186, s0, v141
	v_subrev_u32_e32 v190, s0, v142
	v_subrev_u32_e32 v116, s0, v143
	v_subrev_u32_e32 v117, s0, v144
	v_subrev_u32_e32 v114, s0, v145
	v_subrev_u32_e32 v115, s0, v146
	v_subrev_u32_e32 v112, s0, v147
	v_subrev_u32_e32 v113, s0, v148
	v_subrev_u32_e32 v110, s0, v149
	v_subrev_u32_e32 v111, s0, v150
	v_subrev_u32_e32 v108, s0, v151
	v_subrev_u32_e32 v109, s0, v152
	v_subrev_u32_e32 v106, s0, v153
	v_subrev_u32_e32 v107, s0, v154
	v_subrev_u32_e32 v104, s0, v155
	v_subrev_u32_e32 v105, s0, v156
	v_subrev_u32_e32 v102, s0, v157
	v_subrev_u32_e32 v103, s0, v158
	v_subrev_u32_e32 v100, s0, v159
	v_subrev_u32_e32 v101, s0, v160
	v_subrev_u32_e32 v98, s0, v161
	v_subrev_u32_e32 v2, s0, v162
	v_subrev_u32_e32 v99, s0, v164
	v_subrev_u32_e32 v170, s0, v165
	v_cmp_lt_i32_e64 s[0:1], s36, v175
	v_sub_f32_e32 v0, v0, v1
	s_and_b64 vcc, vcc, s[0:1]
	v_mov_b32_e32 v48, v45
	v_add_u32_e32 v170, v191, v170
	v_cndmask_b32_e32 v174, v234, v0, vcc
	v_pk_mul_f32 v[0:1], v[48:49], v[200:201]
	v_cvt_f32_i32_e32 v201, v170
	v_cmp_gt_u32_e32 vcc, s69, v171
	v_cmp_le_i32_e64 s[0:1], s36, v175
	v_sub_f32_e32 v0, v0, v1
	s_and_b64 vcc, vcc, s[0:1]
	v_mov_b32_e32 v48, v46
	v_add_u32_e32 v99, v191, v99
	v_cndmask_b32_e32 v173, v234, v0, vcc
	v_or_b32_e32 v176, 2, v175
	v_pk_mul_f32 v[0:1], v[48:49], v[200:201]
	v_cvt_f32_i32_e32 v201, v99
	v_cmp_gt_u32_e32 vcc, s69, v170
	v_cmp_lt_i32_e64 s[0:1], s36, v176
	v_sub_f32_e32 v0, v0, v1
	s_and_b64 vcc, vcc, s[0:1]
	v_or_b32_e32 v170, 3, v175
	v_cndmask_b32_e32 v176, v234, v0, vcc
	v_mov_b32_e32 v48, v47
	v_cmp_gt_u32_e32 vcc, s69, v99
	v_cmp_lt_i32_e64 s[0:1], s36, v170
	v_pk_mul_f32 v[0:1], v[48:49], v[200:201]
	s_and_b64 vcc, vcc, s[0:1]
	s_sub_i32 s0, s30, s81
	v_sub_f32_e32 v0, v0, v1
	v_add_u32_e32 v99, s0, v163
	v_cndmask_b32_e32 v175, v234, v0, vcc
	v_add_co_u32_e32 v0, vcc, s69, v99
	v_cvt_f32_i32_e32 v201, v0
	v_mov_b32_e32 v48, v40
	v_add_u32_e32 v178, 0x7f, v99
	v_max3_f32 v171, v57, v174, v173
	v_pk_mul_f32 v[0:1], v[48:49], v[200:201]
	v_cvt_f32_i32_e32 v201, v178
	v_max3_f32 v170, v171, v176, v175
	v_or_b32_e32 v171, s81, v54
	v_cmp_lt_i32_e64 s[0:1], s36, v171
	v_sub_f32_e32 v0, v0, v1
	s_and_b64 vcc, vcc, s[0:1]
	v_mov_b32_e32 v48, v41
	v_add_u32_e32 v183, 0x7e, v99
	v_cndmask_b32_e32 v177, v234, v0, vcc
	v_pk_mul_f32 v[0:1], v[48:49], v[200:201]
	v_cvt_f32_i32_e32 v201, v183
	v_cmp_gt_u32_e32 vcc, s69, v178
	v_cmp_le_i32_e64 s[0:1], s36, v171
	v_sub_f32_e32 v0, v0, v1
	s_and_b64 vcc, vcc, s[0:1]
	v_mov_b32_e32 v48, v42
	v_add_u32_e32 v99, 0x7d, v99
	v_cndmask_b32_e32 v178, v234, v0, vcc
	v_or_b32_e32 v184, 2, v171
	v_pk_mul_f32 v[0:1], v[48:49], v[200:201]
	v_cvt_f32_i32_e32 v201, v99
	v_cmp_gt_u32_e32 vcc, s69, v183
	v_cmp_lt_i32_e64 s[0:1], s36, v184
	v_sub_f32_e32 v0, v0, v1
	s_and_b64 vcc, vcc, s[0:1]
	v_cndmask_b32_e32 v183, v234, v0, vcc
	v_mov_b32_e32 v48, v43
	v_cmp_gt_u32_e32 vcc, s69, v99
	v_add_u32_e32 v99, v191, v2
	v_pk_mul_f32 v[0:1], v[48:49], v[200:201]
	v_cvt_f32_i32_e32 v201, v99
	v_or_b32_e32 v171, 3, v171
	v_cmp_lt_i32_e64 s[0:1], s36, v171
	v_sub_f32_e32 v0, v0, v1
	s_and_b64 vcc, vcc, s[0:1]
	v_mov_b32_e32 v48, v36
	v_cndmask_b32_e32 v184, v234, v0, vcc
	v_pk_mul_f32 v[0:1], v[48:49], v[200:201]
	v_or_b32_e32 v2, s27, v54
	v_sub_f32_e32 v0, v0, v1
	v_add_u32_e32 v1, v191, v98
	v_cvt_f32_i32_e32 v201, v1
	v_cmp_gt_u32_e32 vcc, s69, v99
	v_cmp_lt_i32_e64 s[0:1], s36, v2
	v_mov_b32_e32 v48, v37
	v_add_u32_e32 v101, v191, v101
	s_and_b64 vcc, vcc, s[0:1]
	v_pk_mul_f32 v[98:99], v[48:49], v[200:201]
	v_cvt_f32_i32_e32 v201, v101
	v_cndmask_b32_e32 v0, v234, v0, vcc
	v_cmp_gt_u32_e32 vcc, s69, v1
	v_cmp_le_i32_e64 s[0:1], s36, v2
	v_sub_f32_e32 v48, v98, v99
	s_and_b64 vcc, vcc, s[0:1]
	v_cndmask_b32_e32 v1, v234, v48, vcc
	v_mov_b32_e32 v48, v38
	v_pk_mul_f32 v[98:99], v[48:49], v[200:201]
	v_or_b32_e32 v171, 2, v2
	v_sub_f32_e32 v48, v98, v99
	v_add_u32_e32 v99, v191, v100
	v_cvt_f32_i32_e32 v201, v99
	v_cmp_gt_u32_e32 vcc, s69, v101
	v_cmp_lt_i32_e64 s[0:1], s36, v171
	s_and_b64 vcc, vcc, s[0:1]
	v_cndmask_b32_e32 v98, v234, v48, vcc
	v_mov_b32_e32 v48, v39
	v_add_u32_e32 v103, v191, v103
	v_or_b32_e32 v171, 3, v2
	v_pk_mul_f32 v[100:101], v[48:49], v[200:201]
	v_cvt_f32_i32_e32 v201, v103
	v_cmp_gt_u32_e32 vcc, s69, v99
	v_cmp_lt_i32_e64 s[0:1], s36, v171
	v_sub_f32_e32 v48, v100, v101
	s_and_b64 vcc, vcc, s[0:1]
	v_cndmask_b32_e32 v99, v234, v48, vcc
	v_mov_b32_e32 v48, v28
	v_pk_mul_f32 v[100:101], v[48:49], v[200:201]
	v_or_b32_e32 v171, s26, v54
	v_sub_f32_e32 v48, v100, v101
	v_add_u32_e32 v101, v191, v102
	v_cvt_f32_i32_e32 v201, v101
	v_cmp_gt_u32_e32 vcc, s69, v103
	v_cmp_lt_i32_e64 s[0:1], s36, v171
	s_and_b64 vcc, vcc, s[0:1]
	v_cndmask_b32_e32 v100, v234, v48, vcc
	v_mov_b32_e32 v48, v29
	v_add_u32_e32 v105, v191, v105
	v_pk_mul_f32 v[102:103], v[48:49], v[200:201]
	v_cvt_f32_i32_e32 v201, v105
	v_cmp_gt_u32_e32 vcc, s69, v101
	v_cmp_le_i32_e64 s[0:1], s36, v171
	v_sub_f32_e32 v48, v102, v103
	s_and_b64 vcc, vcc, s[0:1]
	v_cndmask_b32_e32 v101, v234, v48, vcc
	v_mov_b32_e32 v48, v30
	v_pk_mul_f32 v[102:103], v[48:49], v[200:201]
	v_or_b32_e32 v192, 2, v171
	v_sub_f32_e32 v48, v102, v103
	v_add_u32_e32 v103, v191, v104
	v_cvt_f32_i32_e32 v201, v103
	v_cmp_gt_u32_e32 vcc, s69, v105
	v_cmp_lt_i32_e64 s[0:1], s36, v192
	s_and_b64 vcc, vcc, s[0:1]
	v_cndmask_b32_e32 v102, v234, v48, vcc
	v_mov_b32_e32 v48, v31
	v_add_u32_e32 v107, v191, v107
	v_or_b32_e32 v171, 3, v171
	v_pk_mul_f32 v[104:105], v[48:49], v[200:201]
	v_cvt_f32_i32_e32 v201, v107
	v_max3_f32 v170, v170, v177, v178
	v_cmp_gt_u32_e32 vcc, s69, v103
	v_cmp_lt_i32_e64 s[0:1], s36, v171
	v_max3_f32 v170, v170, v183, v184
	v_sub_f32_e32 v48, v104, v105
	s_and_b64 vcc, vcc, s[0:1]
	v_max3_f32 v170, v170, v0, v1
	v_cndmask_b32_e32 v103, v234, v48, vcc
	v_mov_b32_e32 v48, v24
	v_max3_f32 v170, v170, v98, v99
	v_pk_mul_f32 v[104:105], v[48:49], v[200:201]
	v_max3_f32 v170, v170, v100, v101
	v_sub_f32_e32 v48, v104, v105
	v_add_u32_e32 v105, v191, v106
	v_max3_f32 v171, v170, v102, v103
	v_or_b32_e32 v170, s25, v54
	v_cvt_f32_i32_e32 v201, v105
	v_cmp_gt_u32_e32 vcc, s69, v107
	v_cmp_lt_i32_e64 s[0:1], s36, v170
	s_and_b64 vcc, vcc, s[0:1]
	v_cndmask_b32_e32 v104, v234, v48, vcc
	v_mov_b32_e32 v48, v25
	v_add_u32_e32 v109, v191, v109
	v_pk_mul_f32 v[106:107], v[48:49], v[200:201]
	v_cvt_f32_i32_e32 v201, v109
	v_cmp_gt_u32_e32 vcc, s69, v105
	v_cmp_le_i32_e64 s[0:1], s36, v170
	v_sub_f32_e32 v48, v106, v107
	s_and_b64 vcc, vcc, s[0:1]
	v_cndmask_b32_e32 v105, v234, v48, vcc
	v_mov_b32_e32 v48, v26
	v_pk_mul_f32 v[106:107], v[48:49], v[200:201]
	v_or_b32_e32 v192, 2, v170
	v_sub_f32_e32 v48, v106, v107
	v_add_u32_e32 v107, v191, v108
	v_cvt_f32_i32_e32 v201, v107
	v_cmp_gt_u32_e32 vcc, s69, v109
	v_cmp_lt_i32_e64 s[0:1], s36, v192
	s_and_b64 vcc, vcc, s[0:1]
	v_cndmask_b32_e32 v106, v234, v48, vcc
	v_mov_b32_e32 v48, v27
	v_add_u32_e32 v111, v191, v111
	v_or_b32_e32 v192, 3, v170
	v_pk_mul_f32 v[108:109], v[48:49], v[200:201]
	v_cvt_f32_i32_e32 v201, v111
	v_cmp_gt_u32_e32 vcc, s69, v107
	v_cmp_lt_i32_e64 s[0:1], s36, v192
	v_sub_f32_e32 v48, v108, v109
	s_and_b64 vcc, vcc, s[0:1]
	v_cndmask_b32_e32 v107, v234, v48, vcc
	v_mov_b32_e32 v48, v20
	v_pk_mul_f32 v[108:109], v[48:49], v[200:201]
	v_or_b32_e32 v192, s24, v54
	v_sub_f32_e32 v48, v108, v109
	v_add_u32_e32 v109, v191, v110
	v_cvt_f32_i32_e32 v201, v109
	v_cmp_gt_u32_e32 vcc, s69, v111
	v_cmp_lt_i32_e64 s[0:1], s36, v192
	s_and_b64 vcc, vcc, s[0:1]
	v_cndmask_b32_e32 v108, v234, v48, vcc
	v_mov_b32_e32 v48, v21
	v_add_u32_e32 v113, v191, v113
	v_pk_mul_f32 v[110:111], v[48:49], v[200:201]
	v_cvt_f32_i32_e32 v201, v113
	v_cmp_gt_u32_e32 vcc, s69, v109
	v_cmp_le_i32_e64 s[0:1], s36, v192
	v_sub_f32_e32 v48, v110, v111
	s_and_b64 vcc, vcc, s[0:1]
	v_cndmask_b32_e32 v109, v234, v48, vcc
	v_mov_b32_e32 v48, v22
	v_pk_mul_f32 v[110:111], v[48:49], v[200:201]
	v_or_b32_e32 v193, 2, v192
	v_sub_f32_e32 v48, v110, v111
	v_add_u32_e32 v111, v191, v112
	v_cvt_f32_i32_e32 v201, v111
	v_cmp_gt_u32_e32 vcc, s69, v113
	v_cmp_lt_i32_e64 s[0:1], s36, v193
	s_and_b64 vcc, vcc, s[0:1]
	v_cndmask_b32_e32 v110, v234, v48, vcc
	v_mov_b32_e32 v48, v23
	v_add_u32_e32 v115, v191, v115
	v_or_b32_e32 v192, 3, v192
	v_pk_mul_f32 v[112:113], v[48:49], v[200:201]
	v_cvt_f32_i32_e32 v201, v115
	v_cmp_gt_u32_e32 vcc, s69, v111
	v_cmp_lt_i32_e64 s[0:1], s36, v192
	v_sub_f32_e32 v48, v112, v113
	s_and_b64 vcc, vcc, s[0:1]
	v_max3_f32 v171, v171, v104, v105
	v_cndmask_b32_e32 v111, v234, v48, vcc
	v_mov_b32_e32 v48, v16
	v_max3_f32 v171, v171, v106, v107
	v_pk_mul_f32 v[112:113], v[48:49], v[200:201]
	v_max3_f32 v171, v171, v108, v109
	v_sub_f32_e32 v48, v112, v113
	v_add_u32_e32 v113, v191, v114
	v_max3_f32 v192, v171, v110, v111
	v_or_b32_e32 v171, s23, v54
	v_cvt_f32_i32_e32 v201, v113
	v_cmp_gt_u32_e32 vcc, s69, v115
	v_cmp_lt_i32_e64 s[0:1], s36, v171
	s_and_b64 vcc, vcc, s[0:1]
	v_cndmask_b32_e32 v112, v234, v48, vcc
	v_mov_b32_e32 v48, v17
	v_add_u32_e32 v117, v191, v117
	v_pk_mul_f32 v[114:115], v[48:49], v[200:201]
	v_cvt_f32_i32_e32 v201, v117
	v_cmp_gt_u32_e32 vcc, s69, v113
	v_cmp_le_i32_e64 s[0:1], s36, v171
	v_sub_f32_e32 v48, v114, v115
	s_and_b64 vcc, vcc, s[0:1]
	v_cndmask_b32_e32 v113, v234, v48, vcc
	v_mov_b32_e32 v48, v18
	v_pk_mul_f32 v[114:115], v[48:49], v[200:201]
	v_or_b32_e32 v193, 2, v171
	v_sub_f32_e32 v48, v114, v115
	v_add_u32_e32 v115, v191, v116
	v_cvt_f32_i32_e32 v201, v115
	v_cmp_gt_u32_e32 vcc, s69, v117
	v_cmp_lt_i32_e64 s[0:1], s36, v193
	s_and_b64 vcc, vcc, s[0:1]
	v_cndmask_b32_e32 v114, v234, v48, vcc
	v_mov_b32_e32 v48, v19
	v_add_u32_e32 v190, v191, v190
	v_or_b32_e32 v193, 3, v171
	v_pk_mul_f32 v[116:117], v[48:49], v[200:201]
	v_cvt_f32_i32_e32 v201, v190
	v_cmp_gt_u32_e32 vcc, s69, v115
	v_cmp_lt_i32_e64 s[0:1], s36, v193
	v_sub_f32_e32 v48, v116, v117
	s_and_b64 vcc, vcc, s[0:1]
	v_cndmask_b32_e32 v115, v234, v48, vcc
	v_mov_b32_e32 v48, v12
	v_pk_mul_f32 v[116:117], v[48:49], v[200:201]
	v_or_b32_e32 v195, s22, v54
	v_sub_f32_e32 v48, v116, v117
	v_add_u32_e32 v117, v191, v186
	v_cvt_f32_i32_e32 v201, v117
	v_cmp_gt_u32_e32 vcc, s69, v190
	v_cmp_lt_i32_e64 s[0:1], s36, v195
	s_and_b64 vcc, vcc, s[0:1]
	v_max3_f32 v192, v192, v112, v113
	v_cndmask_b32_e32 v116, v234, v48, vcc
	v_mov_b32_e32 v48, v13
	v_add_u32_e32 v119, v191, v119
	v_max3_f32 v194, v192, v114, v115
	v_pk_mul_f32 v[192:193], v[48:49], v[200:201]
	v_cvt_f32_i32_e32 v201, v119
	v_cmp_gt_u32_e32 vcc, s69, v117
	v_cmp_le_i32_e64 s[0:1], s36, v195
	v_sub_f32_e32 v48, v192, v193
	s_and_b64 vcc, vcc, s[0:1]
	v_cndmask_b32_e32 v117, v234, v48, vcc
	v_mov_b32_e32 v48, v14
	v_cmp_gt_u32_e32 vcc, s69, v119
	v_add_u32_e32 v119, v191, v118
	v_or_b32_e32 v190, 2, v195
	v_pk_mul_f32 v[192:193], v[48:49], v[200:201]
	v_cvt_f32_i32_e32 v201, v119
	v_cmp_lt_i32_e64 s[0:1], s36, v190
	v_sub_f32_e32 v48, v192, v193
	s_and_b64 vcc, vcc, s[0:1]
	v_or_b32_e32 v190, 3, v195
	v_cndmask_b32_e32 v118, v234, v48, vcc
	v_mov_b32_e32 v48, v15
	v_cmp_lt_i32_e64 s[0:1], s36, v190
	v_add_u32_e32 v190, v191, v172
	v_pk_mul_f32 v[192:193], v[48:49], v[200:201]
	v_cmp_gt_u32_e32 vcc, s69, v119
	v_cvt_f32_i32_e32 v201, v190
	v_sub_f32_e32 v48, v192, v193
	s_and_b64 vcc, vcc, s[0:1]
	v_max3_f32 v186, v194, v116, v117
	v_cndmask_b32_e32 v119, v234, v48, vcc
	v_max3_f32 v194, v186, v118, v119
	v_mov_b32_e32 v48, v8
	v_add_u32_e32 v186, v191, v185
	v_or_b32_e32 v172, s21, v54
	v_pk_mul_f32 v[192:193], v[48:49], v[200:201]
	v_cvt_f32_i32_e32 v201, v186
	v_cmp_gt_u32_e32 vcc, s69, v190
	v_cmp_lt_i32_e64 s[0:1], s36, v172
	v_sub_f32_e32 v48, v192, v193
	s_and_b64 vcc, vcc, s[0:1]
	v_cndmask_b32_e32 v185, v234, v48, vcc
	v_mov_b32_e32 v48, v9
	v_add_u32_e32 v188, v191, v188
	v_pk_mul_f32 v[192:193], v[48:49], v[200:201]
	v_cvt_f32_i32_e32 v201, v188
	v_cmp_gt_u32_e32 vcc, s69, v186
	v_cmp_le_i32_e64 s[0:1], s36, v172
	v_sub_f32_e32 v48, v192, v193
	s_and_b64 vcc, vcc, s[0:1]
	v_cndmask_b32_e32 v186, v234, v48, vcc
	v_mov_b32_e32 v48, v10
	v_cmp_gt_u32_e32 vcc, s69, v188
	v_add_u32_e32 v188, v191, v187
	v_max3_f32 v190, v194, v185, v186
	v_or_b32_e32 v194, 2, v172
	v_pk_mul_f32 v[192:193], v[48:49], v[200:201]
	v_cvt_f32_i32_e32 v201, v188
	v_cmp_lt_i32_e64 s[0:1], s36, v194
	v_sub_f32_e32 v48, v192, v193
	s_and_b64 vcc, vcc, s[0:1]
	v_cndmask_b32_e32 v187, v234, v48, vcc
	v_mov_b32_e32 v48, v11
	v_add_u32_e32 v189, v191, v189
	v_or_b32_e32 v194, 3, v172
	v_pk_mul_f32 v[192:193], v[48:49], v[200:201]
	v_cvt_f32_i32_e32 v201, v189
	v_cmp_gt_u32_e32 vcc, s69, v188
	v_cmp_lt_i32_e64 s[0:1], s36, v194
	v_sub_f32_e32 v48, v192, v193
	s_and_b64 vcc, vcc, s[0:1]
	v_cndmask_b32_e32 v188, v234, v48, vcc
	v_mov_b32_e32 v48, v4
	v_add_u32_e32 v123, v191, v123
	v_or_b32_e32 v195, s20, v54
	v_pk_mul_f32 v[192:193], v[48:49], v[200:201]
	v_cvt_f32_i32_e32 v201, v123
	v_cmp_gt_u32_e32 vcc, s69, v189
	v_cmp_lt_i32_e64 s[0:1], s36, v195
	v_sub_f32_e32 v48, v192, v193
	s_and_b64 vcc, vcc, s[0:1]
	v_cndmask_b32_e32 v189, v234, v48, vcc
	v_mov_b32_e32 v48, v5
	v_pk_mul_f32 v[192:193], v[48:49], v[200:201]
	v_cmp_gt_u32_e32 vcc, s69, v123
	v_sub_f32_e32 v48, v192, v193
	v_add_u32_e32 v192, v191, v122
	v_cvt_f32_i32_e32 v201, v192
	v_cmp_le_i32_e64 s[0:1], s36, v195
	s_and_b64 vcc, vcc, s[0:1]
	v_max3_f32 v194, v190, v187, v188
	v_cndmask_b32_e32 v190, v234, v48, vcc
	v_mov_b32_e32 v48, v6
	v_add_u32_e32 v121, v191, v121
	v_max3_f32 v193, v194, v189, v190
	v_or_b32_e32 v194, 2, v195
	v_pk_mul_f32 v[122:123], v[48:49], v[200:201]
	v_cvt_f32_i32_e32 v201, v121
	v_cmp_gt_u32_e32 vcc, s69, v192
	v_cmp_lt_i32_e64 s[0:1], s36, v194
	v_sub_f32_e32 v48, v122, v123
	s_and_b64 vcc, vcc, s[0:1]
	v_cndmask_b32_e32 v191, v234, v48, vcc
	v_or_b32_e32 v192, 3, v195
	v_mov_b32_e32 v48, v7
	v_pk_mul_f32 v[122:123], v[48:49], v[200:201]
	v_cmp_gt_u32_e32 vcc, s69, v121
	v_cmp_lt_i32_e64 s[0:1], s36, v192
	v_sub_f32_e32 v48, v122, v123
	s_and_b64 vcc, vcc, s[0:1]
	v_cndmask_b32_e32 v48, v234, v48, vcc
	v_mul_f32_e32 v122, 0x3e000000, v32
	v_cmp_le_i32_e32 vcc, v54, v120
	v_mul_f32_e32 v123, 0x3e000000, v33
	v_max3_f32 v121, v193, v191, v48
	v_cndmask_b32_e32 v122, v234, v122, vcc
	v_cmp_lt_i32_e32 vcc, v54, v120
	v_pk_mul_f32 v[192:193], v[34:35], s[84:85] op_sel_hi:[1,0]
	s_mov_b64 s[0:1], 0
	v_cndmask_b32_e32 v123, v234, v123, vcc
	v_cmp_le_i32_e32 vcc, v51, v120
	v_max3_f32 v194, v121, v122, v123
	s_nop 0
	v_cndmask_b32_e32 v121, v234, v193, vcc
	v_cmp_le_i32_e32 vcc, v56, v120
	s_nop 1
	v_cndmask_b32_e32 v120, v234, v192, vcc
	v_max3_f32 v192, v194, v120, v121
